# P7: conv taps of each unit staged into 4 KiB of unused LDS by one LDS-DMA per wave in the unit's first K iteration; epilogue reads them with ds_read (no vmcnt waits left in the common epilogue path, n
# baseline (speedup 1.0000x reference)
; #define PG8_STAGE(bufoff, gbase, voff) do { _Pragma("unroll") for (int _i = 0; _i < 2; ++_i) \
;         __builtin_amdgcn_global_load_lds((const unsigned*)((const char*)(gbase) + (voff)[_i]), (PG8_LAS unsigned*)(lds + (bufoff) + ldsw + _i * 8192), 16, 0, 0); } while (0)
; #define PG8_LDA(dst, b, h) do { _Pragma("unroll") for (int m = 0; m < 4; ++m) _Pragma("unroll") for (int k = 0; k < 2; ++k) dst[m][k] = *(const PG8_LAS bf16x8*)(lds + PG8_SA(b, h) + aoff + m * 2048 + k * 1024); } while (0)
; #define PG8_LDB(dst, b, h) do { _Pragma("unroll") for (int n = 0; n < 2; ++n) _Pragma("unroll") for (int k = 0; k < 2; ++k) dst[n][k] = *(const PG8_LAS bf16x8*)(lds + PG8_SB(b, h) + boff + n * 2048 + k * 1024); } while (0)
; #define PG8_WAIT_V(n) asm volatile("s_waitcnt vmcnt(" #n ")" ::: "memory")
; #define PG8_WAIT_L(n) asm volatile("s_waitcnt lgkmcnt(" #n ")" ::: "memory")
; #define PG8_BAR __builtin_amdgcn_s_barrier()
; #define PG8_SCHED __builtin_amdgcn_sched_barrier(0)
;     __device__ __forceinline__ void operator()(const f32x4 (&acc)[2][2][4][2], const Unit& u, int wr, int wc, int fr, int fq) const {
;     ...
;         for (int bj = 0; bj < 2; ++bj) { const int col = bj * FF + gcol;
;             w0[bj] = *(const f32x4*)(cw + col); w1[bj] = *(const f32x4*)(cw + FF2 + col); w2[bj] = *(const f32x4*)(cw + 2 * FF2 + col); bb[bj] = *(const f32x4*)(cb + col); }
; template <class Epi, class Sched, bool ALIGN_EPI = false, bool SP2 = false>
; __device__ __forceinline__ void gemm_phase(PG8_LAS unsigned char* lds, const Gemm g, const Sched& S, const Epi& E, int wave_in) {
;     ...
;             PG8_LDB(B0, 0, 0); PG8_LDB(B1, 0, 1); PG8_SCHED; PG8_LDA(At, 0, 0); PG8_STAGE(PG8_SA(1, 1), a1 + hstep, voffA);
;             PG8_WAIT_V(8); PG8_WAIT_L(0); PG8_BAR; PG8_MMA(0, 0, At, B0); PG8_MMA(0, 1, At, B1); PG8_BAR; PG8_SCHED;
;             PG8_LDA(At, 0, 1); PG8_STAGE(PG8_SB(0, 0), b2, voffB); PG8_STAGE(PG8_SB(0, 1), b2 + hstep, voffB); PG8_STAGE(PG8_SA(0, 0), a2, voffA);
;             PG8_WAIT_V(8); PG8_WAIT_L(0); PG8_BAR; PG8_MMA(1, 0, At, B0); PG8_MMA(1, 1, At, B1); PG8_BAR; PG8_SCHED;
;             PG8_LDB(B0, 1, 0); PG8_LDB(B1, 1, 1); PG8_SCHED; PG8_LDA(At, 1, 0); PG8_STAGE(PG8_SA(0, 1), a2 + hstep, voffA);
;             PG8_WAIT_V(8); PG8_WAIT_L(0); PG8_BAR; PG8_MMA(0, 0, At, B0); PG8_MMA(0, 1, At, B1); PG8_BAR; PG8_SCHED;
.LBB0_896:
	s_ashr_i32 s11, s10, 31
	s_lshl_b64 s[18:19], s[10:11], 19
	s_add_u32 s66, s6, s18
	s_addc_u32 s67, s72, s19
	s_and_b64 s[18:19], s[46:47], exec
	s_cselect_b32 s11, s67, s1
	s_cselect_b32 s34, s66, s0
	s_ashr_i32 s5, s4, 31
	s_lshl_b64 s[18:19], s[4:5], 19
	s_add_u32 s38, s73, s18
	s_addc_u32 s39, s74, s19
	s_and_b64 s[18:19], s[46:47], exec
	s_cselect_b32 s5, s39, s79
	s_cselect_b32 s53, s38, s78
	s_add_u32 s81, s78, 0x100
	s_addc_u32 s18, s79, 0
	s_add_u32 vcc_lo, s0, 0x40080
	s_addc_u32 vcc_hi, s1, 0
	s_mov_b32 s19, -2
	s_add_u32 s0, vcc_lo, 0xfffc0080
	s_addc_u32 s1, vcc_hi, -1
	s_add_i32 s76, s35, 0x100
	s_cmp_eq_u32 s19, 12
	s_cselect_b32 s79, s11, s1
	s_cselect_b32 s78, s34, s0
	s_cselect_b32 s1, s5, s18
	s_cselect_b32 s0, s53, s81
	s_add_i32 s29, s90, 0x100
	v_add_u32_e32 v140, s76, v207
	v_add_u32_e32 v156, s29, v207
	ds_read_b128 v[128:131], v140
	ds_read_b128 v[132:135], v140 offset:1024
	ds_read_b128 v[136:139], v140 offset:2048
	ds_read_b128 v[140:143], v140 offset:3072
	ds_read_b128 v[144:147], v156
	ds_read_b128 v[148:151], v156 offset:1024
	ds_read_b128 v[152:155], v156 offset:2048
	ds_read_b128 v[156:159], v156 offset:3072
	v_lshl_add_u64 v[190:191], vcc, 0, v[176:177]
	s_add_i32 m0, s33, 0xc000
	ds_read_b128 v[160:163], v219
	ds_read_b128 v[164:167], v219 offset:1024
	ds_read_b128 v[178:181], v219 offset:2048
	ds_read_b128 v[182:185], v219 offset:3072
	ds_read_b128 v[186:189], v219 offset:4096
	ds_read_b128 v[198:201], v219 offset:5120
	ds_read_b128 v[202:205], v219 offset:6144
	ds_read_b128 v[220:223], v219 offset:7168
	global_load_lds_dwordx4 v[190:191], off
	v_lshl_add_u64 v[190:191], vcc, 0, v[174:175]
	s_add_i32 m0, s33, 0xe000
	s_nop 0
	global_load_lds_dwordx4 v[190:191], off
	s_waitcnt vmcnt(8)
	s_waitcnt lgkmcnt(0)
	s_barrier
	s_setprio 1
	s_waitcnt lgkmcnt(0)
	v_mfma_f32_16x16x32_bf16 v[124:127], v[128:131], v[160:163], 0
	v_mfma_f32_16x16x32_bf16 v[60:63], v[136:139], v[160:163], 0
	v_mfma_f32_16x16x32_bf16 v[116:119], v[128:131], v[178:181], 0
	v_mfma_f32_16x16x32_bf16 v[52:55], v[136:139], v[178:181], 0
	v_mfma_f32_16x16x32_bf16 v[108:111], v[128:131], v[186:189], 0
	v_mfma_f32_16x16x32_bf16 v[44:47], v[136:139], v[186:189], 0
	v_mfma_f32_16x16x32_bf16 v[100:103], v[128:131], v[202:205], 0
	v_mfma_f32_16x16x32_bf16 v[36:39], v[136:139], v[202:205], 0
	v_mfma_f32_16x16x32_bf16 v[124:127], v[132:135], v[164:167], v[124:127]
	v_mfma_f32_16x16x32_bf16 v[60:63], v[140:143], v[164:167], v[60:63]
	v_mfma_f32_16x16x32_bf16 v[116:119], v[132:135], v[182:185], v[116:119]
	v_mfma_f32_16x16x32_bf16 v[52:55], v[140:143], v[182:185], v[52:55]
	v_mfma_f32_16x16x32_bf16 v[108:111], v[132:135], v[198:201], v[108:111]
	v_mfma_f32_16x16x32_bf16 v[44:47], v[140:143], v[198:201], v[44:47]
	v_mfma_f32_16x16x32_bf16 v[100:103], v[132:135], v[220:223], v[100:103]
	v_mfma_f32_16x16x32_bf16 v[36:39], v[140:143], v[220:223], v[36:39]
	s_setprio 0
	s_setprio 1
	v_mfma_f32_16x16x32_bf16 v[120:123], v[144:147], v[160:163], 0
	v_mfma_f32_16x16x32_bf16 v[56:59], v[152:155], v[160:163], 0
	v_mfma_f32_16x16x32_bf16 v[112:115], v[144:147], v[178:181], 0
	v_mfma_f32_16x16x32_bf16 v[48:51], v[152:155], v[178:181], 0
	v_mfma_f32_16x16x32_bf16 v[104:107], v[144:147], v[186:189], 0
	v_mfma_f32_16x16x32_bf16 v[40:43], v[152:155], v[186:189], 0
	v_mfma_f32_16x16x32_bf16 v[96:99], v[144:147], v[202:205], 0
	v_mfma_f32_16x16x32_bf16 v[32:35], v[152:155], v[202:205], 0
	v_mfma_f32_16x16x32_bf16 v[120:123], v[148:151], v[164:167], v[120:123]
	v_mfma_f32_16x16x32_bf16 v[56:59], v[156:159], v[164:167], v[56:59]
	v_mfma_f32_16x16x32_bf16 v[112:115], v[148:151], v[182:185], v[112:115]
	v_mfma_f32_16x16x32_bf16 v[48:51], v[156:159], v[182:185], v[48:51]
	v_mfma_f32_16x16x32_bf16 v[104:107], v[148:151], v[198:201], v[104:107]
	v_mfma_f32_16x16x32_bf16 v[40:43], v[156:159], v[198:201], v[40:43]
	v_mfma_f32_16x16x32_bf16 v[96:99], v[148:151], v[220:223], v[96:99]
	v_mfma_f32_16x16x32_bf16 v[32:35], v[156:159], v[220:223], v[32:35]
	s_setprio 0
	s_barrier
	v_readfirstlane_b32 s83, v208
	s_lshl_b32 s82, s69, 9
	v_and_b32_e32 v212, 31, v252
	v_and_b32_e32 v249, 32, v252
	v_lshlrev_b32_e32 v212, 4, v212
	v_mul_u32_u24_e32 v249, 0x160, v249
	s_cmp_eq_u32 s83, 32
	s_cselect_b32 s42, s16, s14
	s_cselect_b32 s43, s17, s15
	s_cmp_eq_u32 s83, 64
	s_cselect_b32 s42, s92, s42
	s_cselect_b32 s43, s93, s43
	s_cmp_eq_u32 s83, 0x60
	s_cselect_b32 s42, s60, s42
	s_cselect_b32 s43, s61, s43
	s_add_u32 s42, s42, s82
	s_addc_u32 s43, s43, 0
	v_add_u32_e32 v212, v212, v249
	s_lshl_b32 s83, s83, 5
	s_add_i32 m0, s83, 0x20100
	s_nop 0
	global_load_lds_dwordx4 v212, s[42:43]
	s_add_i32 s76, s76, s75
	v_lshl_add_u64 v[190:191], s[0:1], 0, v[192:193]
	s_mov_b32 m0, s76
	ds_read_b128 v[160:163], v219 offset:16384
	ds_read_b128 v[164:167], v219 offset:17408
	ds_read_b128 v[178:181], v219 offset:18432
	ds_read_b128 v[182:185], v219 offset:19456
	ds_read_b128 v[186:189], v219 offset:20480
	ds_read_b128 v[198:201], v219 offset:21504
	ds_read_b128 v[202:205], v219 offset:22528
	ds_read_b128 v[220:223], v219 offset:23552
	global_load_lds_dwordx4 v[190:191], off
	s_add_i32 m0, s76, 0x2000
	s_add_u32 s76, s0, 0x40000
	v_lshl_add_u64 v[194:195], s[0:1], 0, v[168:169]
	s_addc_u32 s77, s1, 0
	s_add_i32 s29, s29, s75
	global_load_lds_dwordx4 v[194:195], off
	v_lshl_add_u64 v[196:197], s[76:77], 0, v[192:193]
	s_mov_b32 m0, s29
	v_lshl_add_u64 v[224:225], s[78:79], 0, v[170:171]
	global_load_lds_dwordx4 v[196:197], off
	v_lshl_add_u64 v[196:197], s[76:77], 0, v[168:169]
	s_add_i32 m0, s29, 0x2000
	s_nop 0
	global_load_lds_dwordx4 v[196:197], off
	v_lshl_add_u64 v[196:197], s[78:79], 0, v[172:173]
	s_mov_b32 m0, s33
	s_nop 0
	global_load_lds_dwordx4 v[196:197], off
	s_mov_b32 m0, s62
	s_nop 0
	global_load_lds_dwordx4 v[224:225], off
	s_waitcnt vmcnt(8)
	s_waitcnt lgkmcnt(0)
	s_barrier
; #define PG8_STAGE(bufoff, gbase, voff) do { _Pragma("unroll") for (int _i = 0; _i < 2; ++_i) \
;         __builtin_amdgcn_global_load_lds((const unsigned*)((const char*)(gbase) + (voff)[_i]), (PG8_LAS unsigned*)(lds + (bufoff) + ldsw + _i * 8192), 16, 0, 0); } while (0)
; #define PG8_LDA(dst, b, h) do { _Pragma("unroll") for (int m = 0; m < 4; ++m) _Pragma("unroll") for (int k = 0; k < 2; ++k) dst[m][k] = *(const PG8_LAS bf16x8*)(lds + PG8_SA(b, h) + aoff + m * 2048 + k * 1024); } while (0)
; #define PG8_LDB(dst, b, h) do { _Pragma("unroll") for (int n = 0; n < 2; ++n) _Pragma("unroll") for (int k = 0; k < 2; ++k) dst[n][k] = *(const PG8_LAS bf16x8*)(lds + PG8_SB(b, h) + boff + n * 2048 + k * 1024); } while (0)
; #define PG8_MMA(ai, bj, At, Bt) do { __builtin_amdgcn_s_setprio(1); _Pragma("unroll") for (int m = 0; m < 4; ++m) _Pragma("unroll") for (int n = 0; n < 2; ++n) _Pragma("unroll") for (int k = 0; k < 2; ++k) \
;         acc[ai][bj][m][n] = __builtin_amdgcn_mfma_f32_16x16x32_bf16(Bt[n][k], At[m][k], acc[ai][bj][m][n], 0, 0, 0); __builtin_amdgcn_s_setprio(0); } while (0)
; #define PG8_WAIT_V(n) asm volatile("s_waitcnt vmcnt(" #n ")" ::: "memory")
; #define PG8_WAIT_L(n) asm volatile("s_waitcnt lgkmcnt(" #n ")" ::: "memory")
; #define PG8_BAR __builtin_amdgcn_s_barrier()
; #define PG8_SCHED __builtin_amdgcn_sched_barrier(0)
; template <class Epi, class Sched, bool ALIGN_EPI = false, bool SP2 = false>
; __device__ __forceinline__ void gemm_phase(PG8_LAS unsigned char* lds, const Gemm g, const Sched& S, const Epi& E, int wave_in) {
;     ...
;             PG8_LDA(At, 0, 1); PG8_STAGE(PG8_SB(0, 0), b2, voffB); PG8_STAGE(PG8_SB(0, 1), b2 + hstep, voffB); PG8_STAGE(PG8_SA(0, 0), a2, voffA);
;             PG8_WAIT_V(8); PG8_WAIT_L(0); PG8_BAR; PG8_MMA(1, 0, At, B0); PG8_MMA(1, 1, At, B1); PG8_BAR; PG8_SCHED;
;             PG8_LDB(B0, 1, 0); PG8_LDB(B1, 1, 1); PG8_SCHED; PG8_LDA(At, 1, 0); PG8_STAGE(PG8_SA(0, 1), a2 + hstep, voffA);
;             PG8_WAIT_V(8); PG8_WAIT_L(0); PG8_BAR; PG8_MMA(0, 0, At, B0); PG8_MMA(0, 1, At, B1); PG8_BAR; PG8_SCHED;
	s_setprio 1
	s_waitcnt lgkmcnt(0)
	v_mfma_f32_16x16x32_bf16 v[92:95], v[128:131], v[160:163], 0
	v_mfma_f32_16x16x32_bf16 v[28:31], v[136:139], v[160:163], 0
	v_mfma_f32_16x16x32_bf16 v[84:87], v[128:131], v[178:181], 0
	v_mfma_f32_16x16x32_bf16 v[20:23], v[136:139], v[178:181], 0
	v_mfma_f32_16x16x32_bf16 v[76:79], v[128:131], v[186:189], 0
	v_mfma_f32_16x16x32_bf16 v[12:15], v[136:139], v[186:189], 0
	v_mfma_f32_16x16x32_bf16 v[68:71], v[128:131], v[202:205], 0
	v_mfma_f32_16x16x32_bf16 v[4:7], v[136:139], v[202:205], 0
	v_mfma_f32_16x16x32_bf16 v[92:95], v[132:135], v[164:167], v[92:95]
	v_mfma_f32_16x16x32_bf16 v[28:31], v[140:143], v[164:167], v[28:31]
	v_mfma_f32_16x16x32_bf16 v[84:87], v[132:135], v[182:185], v[84:87]
	v_mfma_f32_16x16x32_bf16 v[20:23], v[140:143], v[182:185], v[20:23]
	v_mfma_f32_16x16x32_bf16 v[76:79], v[132:135], v[198:201], v[76:79]
	v_mfma_f32_16x16x32_bf16 v[12:15], v[140:143], v[198:201], v[12:15]
	v_mfma_f32_16x16x32_bf16 v[68:71], v[132:135], v[220:223], v[68:71]
	v_mfma_f32_16x16x32_bf16 v[4:7], v[140:143], v[220:223], v[4:7]
	s_setprio 0
	s_setprio 1
	v_mfma_f32_16x16x32_bf16 v[88:91], v[144:147], v[160:163], 0
	v_mfma_f32_16x16x32_bf16 v[24:27], v[152:155], v[160:163], 0
	v_mfma_f32_16x16x32_bf16 v[80:83], v[144:147], v[178:181], 0
	v_mfma_f32_16x16x32_bf16 v[16:19], v[152:155], v[178:181], 0
	v_mfma_f32_16x16x32_bf16 v[72:75], v[144:147], v[186:189], 0
	v_mfma_f32_16x16x32_bf16 v[8:11], v[152:155], v[186:189], 0
	v_mfma_f32_16x16x32_bf16 v[64:67], v[144:147], v[202:205], 0
	v_mfma_f32_16x16x32_bf16 v[0:3], v[152:155], v[202:205], 0
	v_mfma_f32_16x16x32_bf16 v[88:91], v[148:151], v[164:167], v[88:91]
	v_mfma_f32_16x16x32_bf16 v[24:27], v[156:159], v[164:167], v[24:27]
	v_mfma_f32_16x16x32_bf16 v[80:83], v[148:151], v[182:185], v[80:83]
	v_mfma_f32_16x16x32_bf16 v[16:19], v[156:159], v[182:185], v[16:19]
	v_mfma_f32_16x16x32_bf16 v[72:75], v[148:151], v[198:201], v[72:75]
	v_mfma_f32_16x16x32_bf16 v[8:11], v[156:159], v[198:201], v[8:11]
	v_mfma_f32_16x16x32_bf16 v[64:67], v[148:151], v[220:223], v[64:67]
	v_mfma_f32_16x16x32_bf16 v[0:3], v[156:159], v[220:223], v[0:3]
	s_setprio 0
	s_barrier
	s_add_i32 s29, s65, 0x100
	s_add_i32 s2, s52, 0x100
	v_add_u32_e32 v140, s29, v207
	v_add_u32_e32 v156, s2, v207
	ds_read_b128 v[128:131], v140
	ds_read_b128 v[132:135], v140 offset:1024
	ds_read_b128 v[136:139], v140 offset:2048
	ds_read_b128 v[140:143], v140 offset:3072
	ds_read_b128 v[144:147], v156
	ds_read_b128 v[148:151], v156 offset:1024
	ds_read_b128 v[152:155], v156 offset:2048
	ds_read_b128 v[156:159], v156 offset:3072
	s_add_u32 s76, s78, 0x40000
	s_addc_u32 s77, s79, 0
	s_mov_b32 m0, s63
	v_lshl_add_u64 v[226:227], s[76:77], 0, v[172:173]
	ds_read_b128 v[160:163], v219 offset:32768
	ds_read_b128 v[164:167], v219 offset:33792
	ds_read_b128 v[178:181], v219 offset:34816
	ds_read_b128 v[182:185], v219 offset:35840
	ds_read_b128 v[186:189], v219 offset:36864
	ds_read_b128 v[198:201], v219 offset:37888
	ds_read_b128 v[202:205], v219 offset:38912
	ds_read_b128 v[220:223], v219 offset:39936
	global_load_lds_dwordx4 v[226:227], off
	v_lshl_add_u64 v[226:227], s[76:77], 0, v[170:171]
	s_mov_b32 m0, s31
	s_nop 0
	global_load_lds_dwordx4 v[226:227], off
	s_waitcnt vmcnt(8)
	s_waitcnt lgkmcnt(0)
	s_barrier
	s_setprio 1
	s_waitcnt lgkmcnt(0)
	v_mfma_f32_16x16x32_bf16 v[124:127], v[128:131], v[160:163], v[124:127]
	v_mfma_f32_16x16x32_bf16 v[60:63], v[136:139], v[160:163], v[60:63]
	v_mfma_f32_16x16x32_bf16 v[116:119], v[128:131], v[178:181], v[116:119]
	v_mfma_f32_16x16x32_bf16 v[52:55], v[136:139], v[178:181], v[52:55]
	v_mfma_f32_16x16x32_bf16 v[108:111], v[128:131], v[186:189], v[108:111]
	v_mfma_f32_16x16x32_bf16 v[44:47], v[136:139], v[186:189], v[44:47]
	v_mfma_f32_16x16x32_bf16 v[100:103], v[128:131], v[202:205], v[100:103]
	v_mfma_f32_16x16x32_bf16 v[36:39], v[136:139], v[202:205], v[36:39]
	v_mfma_f32_16x16x32_bf16 v[124:127], v[132:135], v[164:167], v[124:127]
	v_mfma_f32_16x16x32_bf16 v[60:63], v[140:143], v[164:167], v[60:63]
	v_mfma_f32_16x16x32_bf16 v[116:119], v[132:135], v[182:185], v[116:119]
	v_mfma_f32_16x16x32_bf16 v[52:55], v[140:143], v[182:185], v[52:55]
	v_mfma_f32_16x16x32_bf16 v[108:111], v[132:135], v[198:201], v[108:111]
	v_mfma_f32_16x16x32_bf16 v[44:47], v[140:143], v[198:201], v[44:47]
	v_mfma_f32_16x16x32_bf16 v[100:103], v[132:135], v[220:223], v[100:103]
	v_mfma_f32_16x16x32_bf16 v[36:39], v[140:143], v[220:223], v[36:39]
	s_setprio 0
	s_setprio 1
	v_mfma_f32_16x16x32_bf16 v[120:123], v[144:147], v[160:163], v[120:123]
	v_mfma_f32_16x16x32_bf16 v[56:59], v[152:155], v[160:163], v[56:59]
	v_mfma_f32_16x16x32_bf16 v[112:115], v[144:147], v[178:181], v[112:115]
	v_mfma_f32_16x16x32_bf16 v[48:51], v[152:155], v[178:181], v[48:51]
	v_mfma_f32_16x16x32_bf16 v[104:107], v[144:147], v[186:189], v[104:107]
	v_mfma_f32_16x16x32_bf16 v[40:43], v[152:155], v[186:189], v[40:43]
	v_mfma_f32_16x16x32_bf16 v[96:99], v[144:147], v[202:205], v[96:99]
	v_mfma_f32_16x16x32_bf16 v[32:35], v[152:155], v[202:205], v[32:35]
	v_mfma_f32_16x16x32_bf16 v[120:123], v[148:151], v[164:167], v[120:123]
	v_mfma_f32_16x16x32_bf16 v[56:59], v[156:159], v[164:167], v[56:59]
	v_mfma_f32_16x16x32_bf16 v[112:115], v[148:151], v[182:185], v[112:115]
	v_mfma_f32_16x16x32_bf16 v[48:51], v[156:159], v[182:185], v[48:51]
	v_mfma_f32_16x16x32_bf16 v[104:107], v[148:151], v[198:201], v[104:107]
	v_mfma_f32_16x16x32_bf16 v[40:43], v[156:159], v[198:201], v[40:43]
	v_mfma_f32_16x16x32_bf16 v[96:99], v[148:151], v[220:223], v[96:99]
	v_mfma_f32_16x16x32_bf16 v[32:35], v[156:159], v[220:223], v[32:35]
	s_setprio 0
	s_barrier
; #define PG8_STAGE(bufoff, gbase, voff) do { _Pragma("unroll") for (int _i = 0; _i < 2; ++_i) \
;         __builtin_amdgcn_global_load_lds((const unsigned*)((const char*)(gbase) + (voff)[_i]), (PG8_LAS unsigned*)(lds + (bufoff) + ldsw + _i * 8192), 16, 0, 0); } while (0)
; #define PG8_LDA(dst, b, h) do { _Pragma("unroll") for (int m = 0; m < 4; ++m) _Pragma("unroll") for (int k = 0; k < 2; ++k) dst[m][k] = *(const PG8_LAS bf16x8*)(lds + PG8_SA(b, h) + aoff + m * 2048 + k * 1024); } while (0)
; #define PG8_LDB(dst, b, h) do { _Pragma("unroll") for (int n = 0; n < 2; ++n) _Pragma("unroll") for (int k = 0; k < 2; ++k) dst[n][k] = *(const PG8_LAS bf16x8*)(lds + PG8_SB(b, h) + boff + n * 2048 + k * 1024); } while (0)
; #define PG8_MMA(ai, bj, At, Bt) do { __builtin_amdgcn_s_setprio(1); _Pragma("unroll") for (int m = 0; m < 4; ++m) _Pragma("unroll") for (int n = 0; n < 2; ++n) _Pragma("unroll") for (int k = 0; k < 2; ++k) \
;         acc[ai][bj][m][n] = __builtin_amdgcn_mfma_f32_16x16x32_bf16(Bt[n][k], At[m][k], acc[ai][bj][m][n], 0, 0, 0); __builtin_amdgcn_s_setprio(0); } while (0)
; #define PG8_WAIT_V(n) asm volatile("s_waitcnt vmcnt(" #n ")" ::: "memory")
; #define PG8_WAIT_L(n) asm volatile("s_waitcnt lgkmcnt(" #n ")" ::: "memory")
; #define PG8_BAR __builtin_amdgcn_s_barrier()
; #define PG8_SCHED __builtin_amdgcn_sched_barrier(0)
; template <class Epi, class Sched, bool ALIGN_EPI = false, bool SP2 = false>
; __device__ __forceinline__ void gemm_phase(PG8_LAS unsigned char* lds, const Gemm g, const Sched& S, const Epi& E, int wave_in) {
;     ...
;         for (int t = 0; t < nt; t += 2) {
;     ...
;             PG8_LDB(B0, 1, 0); PG8_LDB(B1, 1, 1); PG8_SCHED; PG8_LDA(At, 1, 0); PG8_STAGE(PG8_SA(0, 1), a2 + hstep, voffA);
;             PG8_WAIT_V(8); PG8_WAIT_L(0); PG8_BAR; PG8_MMA(0, 0, At, B0); PG8_MMA(0, 1, At, B1); PG8_BAR; PG8_SCHED;
;             PG8_LDA(At, 1, 1); PG8_STAGE(PG8_SB(1, 0), b3, voffB); PG8_STAGE(PG8_SB(1, 1), b3 + hstep, voffB); PG8_STAGE(PG8_SA(1, 0), a3, voffA);
;             PG8_WAIT_V(8); PG8_WAIT_L(0); PG8_BAR; PG8_MMA(1, 0, At, B0); PG8_MMA(1, 1, At, B1); PG8_BAR; PG8_SCHED;
	s_add_i32 s29, s29, s75
	v_lshl_add_u64 v[190:191], v[190:191], 0, s[88:89]
	s_mov_b32 m0, s29
	ds_read_b128 v[160:163], v219 offset:49152
	ds_read_b128 v[164:167], v219 offset:50176
	ds_read_b128 v[178:181], v219 offset:51200
	ds_read_b128 v[182:185], v219 offset:52224
	ds_read_b128 v[186:189], v219 offset:53248
	ds_read_b128 v[198:201], v219 offset:54272
	ds_read_b128 v[202:205], v219 offset:55296
	ds_read_b128 v[220:223], v219 offset:56320
	global_load_lds_dwordx4 v[190:191], off
	s_add_i32 m0, s29, 0x2000
	s_add_u32 s0, s0, 0x40080
	v_lshl_add_u64 v[190:191], v[194:195], 0, s[88:89]
	s_addc_u32 s1, s1, 0
	s_add_i32 s2, s2, s75
	global_load_lds_dwordx4 v[190:191], off
	v_lshl_add_u64 v[190:191], s[0:1], 0, v[192:193]
	s_mov_b32 m0, s2
	s_nop 0
	global_load_lds_dwordx4 v[190:191], off
	v_lshl_add_u64 v[190:191], s[0:1], 0, v[168:169]
	s_add_i32 m0, s2, 0x2000
	s_nop 0
	global_load_lds_dwordx4 v[190:191], off
	v_lshl_add_u64 v[190:191], v[196:197], 0, s[88:89]
	s_mov_b32 m0, s9
	s_nop 0
	global_load_lds_dwordx4 v[190:191], off
	v_lshl_add_u64 v[190:191], v[224:225], 0, s[88:89]
	s_mov_b32 m0, s96
	s_nop 0
	global_load_lds_dwordx4 v[190:191], off
	s_waitcnt vmcnt(8)
	s_waitcnt lgkmcnt(0)
	s_barrier
	s_setprio 1
	s_waitcnt lgkmcnt(0)
	v_mfma_f32_16x16x32_bf16 v[92:95], v[128:131], v[160:163], v[92:95]
	v_mfma_f32_16x16x32_bf16 v[28:31], v[136:139], v[160:163], v[28:31]
	v_mfma_f32_16x16x32_bf16 v[84:87], v[128:131], v[178:181], v[84:87]
	v_mfma_f32_16x16x32_bf16 v[20:23], v[136:139], v[178:181], v[20:23]
	v_mfma_f32_16x16x32_bf16 v[76:79], v[128:131], v[186:189], v[76:79]
	v_mfma_f32_16x16x32_bf16 v[12:15], v[136:139], v[186:189], v[12:15]
	v_mfma_f32_16x16x32_bf16 v[68:71], v[128:131], v[202:205], v[68:71]
	v_mfma_f32_16x16x32_bf16 v[4:7], v[136:139], v[202:205], v[4:7]
	v_mfma_f32_16x16x32_bf16 v[92:95], v[132:135], v[164:167], v[92:95]
	v_mfma_f32_16x16x32_bf16 v[28:31], v[140:143], v[164:167], v[28:31]
	v_mfma_f32_16x16x32_bf16 v[84:87], v[132:135], v[182:185], v[84:87]
	v_mfma_f32_16x16x32_bf16 v[20:23], v[140:143], v[182:185], v[20:23]
	v_mfma_f32_16x16x32_bf16 v[76:79], v[132:135], v[198:201], v[76:79]
	v_mfma_f32_16x16x32_bf16 v[12:15], v[140:143], v[198:201], v[12:15]
	v_mfma_f32_16x16x32_bf16 v[68:71], v[132:135], v[220:223], v[68:71]
	v_mfma_f32_16x16x32_bf16 v[4:7], v[140:143], v[220:223], v[4:7]
	s_setprio 0
	s_setprio 1
	v_mfma_f32_16x16x32_bf16 v[88:91], v[144:147], v[160:163], v[88:91]
	v_mfma_f32_16x16x32_bf16 v[24:27], v[152:155], v[160:163], v[24:27]
	v_mfma_f32_16x16x32_bf16 v[80:83], v[144:147], v[178:181], v[80:83]
	v_mfma_f32_16x16x32_bf16 v[16:19], v[152:155], v[178:181], v[16:19]
	v_mfma_f32_16x16x32_bf16 v[72:75], v[144:147], v[186:189], v[72:75]
	v_mfma_f32_16x16x32_bf16 v[8:11], v[152:155], v[186:189], v[8:11]
	v_mfma_f32_16x16x32_bf16 v[64:67], v[144:147], v[202:205], v[64:67]
	v_mfma_f32_16x16x32_bf16 v[0:3], v[152:155], v[202:205], v[0:3]
	v_mfma_f32_16x16x32_bf16 v[88:91], v[148:151], v[164:167], v[88:91]
	v_mfma_f32_16x16x32_bf16 v[24:27], v[156:159], v[164:167], v[24:27]
	v_mfma_f32_16x16x32_bf16 v[80:83], v[148:151], v[182:185], v[80:83]
	v_mfma_f32_16x16x32_bf16 v[16:19], v[156:159], v[182:185], v[16:19]
	v_mfma_f32_16x16x32_bf16 v[72:75], v[148:151], v[198:201], v[72:75]
	v_mfma_f32_16x16x32_bf16 v[8:11], v[156:159], v[198:201], v[8:11]
	v_mfma_f32_16x16x32_bf16 v[64:67], v[148:151], v[220:223], v[64:67]
	v_mfma_f32_16x16x32_bf16 v[0:3], v[156:159], v[220:223], v[0:3]
	s_setprio 0
	s_barrier
	s_add_i32 s19, s19, 2
	s_add_u32 s81, s81, 0x100
	s_addc_u32 s18, s18, 0
	s_add_u32 vcc_lo, vcc_lo, 0x100
	s_addc_u32 vcc_hi, vcc_hi, 0
	s_cmp_gt_u32 s19, 13
	s_cbranch_scc1 .Lkexit_6

; __device__ __forceinline__ void load_rs(const float* slots, int rowbase, int fr, int fq, float scale, float (&rs)[2][4]) {
;     float loc[2];
; #pragma unroll
;     for (int ai = 0; ai < 2; ++ai) loc[ai] = scale * row_rstd(slots, rowbase + ai * HALF + fq * 16 + fr);
; #pragma unroll
;     for (int ai = 0; ai < 2; ++ai)
; #pragma unroll
;         for (int m = 0; m < 4; ++m) rs[ai][m] = __shfl(loc[ai], m * 16 + fr);
;     __device__ __forceinline__ void operator()(const f32x4 (&acc)[2][2][4][2], const Unit& u, int wr, int wc, int fr, int fq) const {
;     ...
;         f32x4 w0[2], w1[2], w2[2], bb[2];
; #pragma unroll
;         for (int bj = 0; bj < 2; ++bj) { const int col = bj * FF + gcol;
;             w0[bj] = *(const f32x4*)(cw + col); w1[bj] = *(const f32x4*)(cw + FF2 + col); w2[bj] = *(const f32x4*)(cw + 2 * FF2 + col); bb[bj] = *(const f32x4*)(cb + col); }
.LBB0_900:
	v_readlane_b32 s18, v255, 37
	v_readlane_b32 s19, v255, 38
	s_lshl_b32 s5, s71, 8
	s_add_i32 s5, s5, s8
	s_lshl_b32 s11, s71, 1
	s_movk_i32 s29, 0x1600
	s_mov_b32 s100, 0xbfb8aa3b
	s_mov_b32 s79, 0
	v_cmp_eq_u32_e64 s[98:99], 15, v206
	v_lshl_or_b32 v233, s69, 7, v208
	v_lshlrev_b32_e32 v237, 2, v206
	v_lshlrev_b32_e32 v233, 2, v233
	v_or_b32_e32 v239, s5, v206
	v_lshlrev_b32_e32 v235, 2, v208
	v_add_u32_e32 v235, 0x20100, v235
	ds_read_b128 v[128:131], v235
	ds_read_b128 v[132:135], v235 offset:1024
	ds_read_b128 v[136:139], v235 offset:2048
	ds_read_b128 v[140:143], v235 offset:3072
	ds_read_b128 v[144:147], v235 offset:512
	ds_read_b128 v[148:151], v235 offset:1536
	ds_read_b128 v[152:155], v235 offset:2560
	ds_read_b128 v[156:159], v235 offset:3584
	v_lshrrev_b32_e32 v243, 1, v233
	v_add_u32_e32 v241, s11, v206
	v_mad_u32_u24 v239, v239, s29, v243
	v_mad_u32_u24 v241, v241, s70, v233
	s_cmp_eq_u32 s101, s71
	v_add_u32_e32 v249, 0x2c00, v241
	s_cbranch_scc1 .Lp7_rsok
	v_or_b32_e32 v229, s5, v209
	v_lshlrev_b32_e32 v229, 6, v229
	v_add_u32_e32 v231, 0x2000, v229
	global_load_dwordx4 v[160:163], v229, s[26:27]
	global_load_dwordx4 v[164:167], v229, s[26:27] offset:16
	global_load_dwordx4 v[178:181], v229, s[26:27] offset:32
	global_load_dwordx4 v[182:185], v229, s[26:27] offset:48
	global_load_dwordx4 v[186:189], v231, s[26:27]
	global_load_dwordx4 v[194:197], v231, s[26:27] offset:16
	global_load_dwordx4 v[198:201], v231, s[26:27] offset:32
	global_load_dwordx4 v[202:205], v231, s[26:27] offset:48
	s_waitcnt vmcnt(0)
	v_pk_add_f32 v[162:163], v[162:163], v[166:167]
	v_pk_add_f32 v[188:189], v[188:189], v[196:197]
	v_pk_add_f32 v[160:161], v[160:161], v[164:165]
	v_pk_add_f32 v[186:187], v[186:187], v[194:195]
	v_pk_add_f32 v[164:165], v[180:181], v[184:185]
	v_pk_add_f32 v[194:195], v[200:201], v[204:205]
	v_pk_add_f32 v[166:167], v[178:179], v[182:183]
	v_pk_add_f32 v[196:197], v[198:199], v[202:203]
	v_pk_add_f32 v[162:163], v[162:163], v[164:165]
	v_pk_add_f32 v[188:189], v[188:189], v[194:195]
	v_pk_add_f32 v[160:161], v[160:161], v[166:167]
	v_pk_add_f32 v[186:187], v[186:187], v[196:197]
	v_add_f32_e32 v160, v160, v161
	v_add_f32_e32 v186, v186, v187
	v_add_f32_e32 v161, v162, v163
	v_add_f32_e32 v187, v188, v189
	v_add_f32_e32 v160, v160, v161
	v_add_f32_e32 v186, v186, v187
	v_fmamk_f32 v160, v160, 0x3a800000, v244
	v_fmamk_f32 v186, v186, 0x3a800000, v244
	v_rsq_f32_e32 v160, v160
	v_rsq_f32_e32 v186, v186
	ds_bpermute_b32 v228, v237, v160
	ds_bpermute_b32 v230, v237, v160 offset:64
	ds_bpermute_b32 v232, v237, v160 offset:128
	ds_bpermute_b32 v234, v237, v160 offset:192
	ds_bpermute_b32 v236, v237, v186
	ds_bpermute_b32 v238, v237, v186 offset:64
	ds_bpermute_b32 v240, v237, v186 offset:128
	ds_bpermute_b32 v248, v237, v186 offset:192
	s_mov_b32 s101, s71

; __device__ __forceinline__ unsigned cvt_pk_bf16(float lo, float hi) { unsigned r; asm volatile("v_cvt_pk_bf16_f32 %0, %1, %2" : "=v"(r) : "v"(lo), "v"(hi)); return r; }
; __device__ __forceinline__ float dpp_ror1(float x) { return __int_as_float(__builtin_amdgcn_update_dpp(0, __float_as_int(x), 0x121, 0xf, 0xf, false)); }
; __device__ __forceinline__ float dpp_ror2(float x) { return __int_as_float(__builtin_amdgcn_update_dpp(0, __float_as_int(x), 0x122, 0xf, 0xf, false)); }
;     __device__ __forceinline__ void operator()(const f32x4 (&acc)[2][2][4][2], const Unit& u, int wr, int wc, int fr, int fq) const {
;     ...
;                 for (int m = 0; m < 4; ++m) {
;                     f32x4 cur[2], h[2];
; #pragma unroll
;                     for (int bj = 0; bj < 2; ++bj) { cur[bj] = acc[ai][bj][m][n] * rs[ai][m]; f32x4 x1, x2;
; #pragma unroll
;                         for (int e = 0; e < 4; ++e) { const float c1 = dpp_ror1(cur[bj][e]), p1 = dpp_ror1(pg[bj][e]), c2 = dpp_ror2(cur[bj][e]), p2 = dpp_ror2(pg[bj][e]);
;                             x1[e] = fr >= 1 ? c1 : p1; x2[e] = fr >= 2 ? c2 : p2; }
;                         h[bj] = bb[bj] + w0[bj] * x2 + w1[bj] * x1 + w2[bj] * cur[bj]; }
;                     if (ai == 0 && wr == 0 && m == 0 && fr < 2) {
;                         *(f32x4*)(hc0 + (size_t)(u.pm * 2 + fr) * FF2 + gcol + 4 * n) = h[0]; *(f32x4*)(hc0 + (size_t)(u.pm * 2 + fr) * FF2 + FF + gcol + 4 * n) = h[1]; }
;                     f32x4 a;
; #pragma unroll
;                     for (int e = 0; e < 4; ++e) { const float g = h[0][e]; a[e] = g * __builtin_amdgcn_rcpf(1.0f + __builtin_amdgcn_exp2f(-1.4426950408889634f * g)) * h[1][e]; }
;                     const unsigned p0 = cvt_pk_bf16(a[0], a[1]), p1 = cvt_pk_bf16(a[2], a[3]);
;                     if (n == 0) { pk_lo[ai][m][0] = p0; pk_lo[ai][m][1] = p1; }
.Lp7_hr0:
	ds_read_b128 v[178:181], v214
	ds_read_b128 v[182:185], v214 offset:512
	v_pk_mul_f32 v[124:125], v[124:125], v[228:229] op_sel_hi:[1,0]
	v_pk_mul_f32 v[126:127], v[126:127], v[228:229] op_sel_hi:[1,0]
	v_pk_mul_f32 v[120:121], v[120:121], v[228:229] op_sel_hi:[1,0]
	v_pk_mul_f32 v[122:123], v[122:123], v[228:229] op_sel_hi:[1,0]
	v_pk_mul_f32 v[116:117], v[116:117], v[230:231] op_sel_hi:[1,0]
	v_pk_mul_f32 v[118:119], v[118:119], v[230:231] op_sel_hi:[1,0]
	v_pk_mul_f32 v[112:113], v[112:113], v[230:231] op_sel_hi:[1,0]
	v_pk_mul_f32 v[114:115], v[114:115], v[230:231] op_sel_hi:[1,0]
	v_pk_mul_f32 v[108:109], v[108:109], v[232:233] op_sel_hi:[1,0]
	v_pk_mul_f32 v[110:111], v[110:111], v[232:233] op_sel_hi:[1,0]
	v_pk_mul_f32 v[104:105], v[104:105], v[232:233] op_sel_hi:[1,0]
	v_pk_mul_f32 v[106:107], v[106:107], v[232:233] op_sel_hi:[1,0]
	v_pk_mul_f32 v[92:93], v[92:93], v[236:237] op_sel_hi:[1,0]
	v_pk_mul_f32 v[94:95], v[94:95], v[236:237] op_sel_hi:[1,0]
	v_pk_mul_f32 v[88:89], v[88:89], v[236:237] op_sel_hi:[1,0]
	v_pk_mul_f32 v[90:91], v[90:91], v[236:237] op_sel_hi:[1,0]
	v_pk_mul_f32 v[84:85], v[84:85], v[238:239] op_sel_hi:[1,0]
	v_pk_mul_f32 v[86:87], v[86:87], v[238:239] op_sel_hi:[1,0]
	v_pk_mul_f32 v[80:81], v[80:81], v[238:239] op_sel_hi:[1,0]
	v_pk_mul_f32 v[82:83], v[82:83], v[238:239] op_sel_hi:[1,0]
	v_pk_mul_f32 v[76:77], v[76:77], v[240:241] op_sel_hi:[1,0]
	v_pk_mul_f32 v[78:79], v[78:79], v[240:241] op_sel_hi:[1,0]
	v_pk_mul_f32 v[72:73], v[72:73], v[240:241] op_sel_hi:[1,0]
	v_pk_mul_f32 v[74:75], v[74:75], v[240:241] op_sel_hi:[1,0]
	v_pk_mul_f32 v[60:61], v[60:61], v[228:229] op_sel_hi:[1,0]
	v_pk_mul_f32 v[62:63], v[62:63], v[228:229] op_sel_hi:[1,0]
	v_pk_mul_f32 v[56:57], v[56:57], v[228:229] op_sel_hi:[1,0]
	v_pk_mul_f32 v[58:59], v[58:59], v[228:229] op_sel_hi:[1,0]
	v_pk_mul_f32 v[52:53], v[52:53], v[230:231] op_sel_hi:[1,0]
	v_pk_mul_f32 v[54:55], v[54:55], v[230:231] op_sel_hi:[1,0]
	v_pk_mul_f32 v[48:49], v[48:49], v[230:231] op_sel_hi:[1,0]
	v_pk_mul_f32 v[50:51], v[50:51], v[230:231] op_sel_hi:[1,0]
	v_pk_mul_f32 v[44:45], v[44:45], v[232:233] op_sel_hi:[1,0]
	v_pk_mul_f32 v[46:47], v[46:47], v[232:233] op_sel_hi:[1,0]
	v_pk_mul_f32 v[40:41], v[40:41], v[232:233] op_sel_hi:[1,0]
	v_pk_mul_f32 v[42:43], v[42:43], v[232:233] op_sel_hi:[1,0]
	v_pk_mul_f32 v[28:29], v[28:29], v[236:237] op_sel_hi:[1,0]
	v_pk_mul_f32 v[30:31], v[30:31], v[236:237] op_sel_hi:[1,0]
	v_pk_mul_f32 v[24:25], v[24:25], v[236:237] op_sel_hi:[1,0]
	v_pk_mul_f32 v[26:27], v[26:27], v[236:237] op_sel_hi:[1,0]
	v_pk_mul_f32 v[20:21], v[20:21], v[238:239] op_sel_hi:[1,0]
	v_pk_mul_f32 v[22:23], v[22:23], v[238:239] op_sel_hi:[1,0]
	v_pk_mul_f32 v[16:17], v[16:17], v[238:239] op_sel_hi:[1,0]
	v_pk_mul_f32 v[18:19], v[18:19], v[238:239] op_sel_hi:[1,0]
	v_pk_mul_f32 v[12:13], v[12:13], v[240:241] op_sel_hi:[1,0]
	v_pk_mul_f32 v[14:15], v[14:15], v[240:241] op_sel_hi:[1,0]
	v_pk_mul_f32 v[8:9], v[8:9], v[240:241] op_sel_hi:[1,0]
	v_pk_mul_f32 v[10:11], v[10:11], v[240:241] op_sel_hi:[1,0]
	s_waitcnt lgkmcnt(0)
	v_pk_fma_f32 v[220:221], v[136:137], v[124:125], v[140:141]
	v_pk_fma_f32 v[222:223], v[138:139], v[126:127], v[142:143]
	v_pk_fma_f32 v[224:225], v[152:153], v[120:121], v[156:157]
	v_pk_fma_f32 v[226:227], v[154:155], v[122:123], v[158:159]
	v_cndmask_b32_e64 v188, v124, v160, s[98:99]
	v_cndmask_b32_e64 v189, v125, v161, s[98:99]
	v_cndmask_b32_e64 v196, v126, v162, s[98:99]
	v_cndmask_b32_e64 v197, v127, v163, s[98:99]
	v_cndmask_b32_e64 v200, v120, v164, s[98:99]
	v_cndmask_b32_e64 v201, v121, v165, s[98:99]
	v_cndmask_b32_e64 v204, v122, v166, s[98:99]
	v_cndmask_b32_e64 v205, v123, v167, s[98:99]
	v_fmac_f32_dpp v220, v188, v132 row_ror:1 row_mask:0xf bank_mask:0xf
	v_fmac_f32_dpp v221, v189, v133 row_ror:1 row_mask:0xf bank_mask:0xf
	v_fmac_f32_dpp v222, v196, v134 row_ror:1 row_mask:0xf bank_mask:0xf
	v_fmac_f32_dpp v223, v197, v135 row_ror:1 row_mask:0xf bank_mask:0xf
	v_fmac_f32_dpp v224, v200, v148 row_ror:1 row_mask:0xf bank_mask:0xf
	v_fmac_f32_dpp v225, v201, v149 row_ror:1 row_mask:0xf bank_mask:0xf
	v_fmac_f32_dpp v226, v204, v150 row_ror:1 row_mask:0xf bank_mask:0xf
	v_fmac_f32_dpp v227, v205, v151 row_ror:1 row_mask:0xf bank_mask:0xf
	v_cndmask_b32_e64 v188, v160, v124, s[40:41]
	v_cndmask_b32_e64 v189, v161, v125, s[40:41]
	v_cndmask_b32_e64 v196, v162, v126, s[40:41]
	v_cndmask_b32_e64 v197, v163, v127, s[40:41]
	v_cndmask_b32_e64 v200, v164, v120, s[40:41]
	v_cndmask_b32_e64 v201, v165, v121, s[40:41]
	v_cndmask_b32_e64 v204, v166, v122, s[40:41]
	v_cndmask_b32_e64 v205, v167, v123, s[40:41]
	v_fmac_f32_dpp v220, v188, v128 row_ror:2 row_mask:0xf bank_mask:0xf
	v_fmac_f32_dpp v221, v189, v129 row_ror:2 row_mask:0xf bank_mask:0xf
	v_fmac_f32_dpp v222, v196, v130 row_ror:2 row_mask:0xf bank_mask:0xf
	v_fmac_f32_dpp v223, v197, v131 row_ror:2 row_mask:0xf bank_mask:0xf
	v_fmac_f32_dpp v224, v200, v144 row_ror:2 row_mask:0xf bank_mask:0xf
	v_fmac_f32_dpp v225, v201, v145 row_ror:2 row_mask:0xf bank_mask:0xf
	v_fmac_f32_dpp v226, v204, v146 row_ror:2 row_mask:0xf bank_mask:0xf
	v_fmac_f32_dpp v227, v205, v147 row_ror:2 row_mask:0xf bank_mask:0xf
	s_and_saveexec_b64 s[0:1], s[12:13]
	global_store_dwordx4 v241, v[220:223], s[84:85]
	global_store_dwordx4 v249, v[224:227], s[84:85]
	s_or_b64 exec, exec, s[0:1]
	v_pk_mul_f32 v[190:191], v[220:221], s[100:101] op_sel_hi:[1,0]
	v_pk_mul_f32 v[250:251], v[222:223], s[100:101] op_sel_hi:[1,0]
	v_exp_f32_e32 v190, v190
	v_exp_f32_e32 v191, v191
	v_exp_f32_e32 v250, v250
	v_exp_f32_e32 v251, v251
	v_pk_mul_f32 v[220:221], v[220:221], v[224:225]
	v_pk_mul_f32 v[222:223], v[222:223], v[226:227]
	v_pk_add_f32 v[190:191], v[190:191], 1.0 op_sel_hi:[1,0]
	v_pk_add_f32 v[250:251], v[250:251], 1.0 op_sel_hi:[1,0]
	v_rcp_f32_e32 v190, v190
	v_rcp_f32_e32 v191, v191
	v_rcp_f32_e32 v250, v250
	v_rcp_f32_e32 v251, v251
	v_pk_mul_f32 v[220:221], v[220:221], v[190:191]
	v_pk_mul_f32 v[222:223], v[222:223], v[250:251]
	v_cvt_pk_bf16_f32 v186, v220, v221
	v_cvt_pk_bf16_f32 v187, v222, v223
	s_and_b64 vcc, exec, s[20:21]
	s_cbranch_vccnz .Lp7_norawh
	s_mov_b64 s[0:1], exec
	s_andn2_b64 exec, exec, s[40:41]
	v_add_u32_e32 v229, s11, v210
	v_mad_u32_u24 v229, v229, s70, v233
	v_add_u32_e32 v231, 0x2c00, v229
	global_store_dwordx4 v229, v[68:71], s[18:19]
	global_store_dwordx4 v229, v[4:7], s[18:19] offset:16
	global_store_dwordx4 v231, v[64:67], s[18:19]
	global_store_dwordx4 v231, v[0:3], s[18:19] offset:16
	s_mov_b64 exec, s[0:1]
; __device__ __forceinline__ unsigned cvt_pk_bf16(float lo, float hi) { unsigned r; asm volatile("v_cvt_pk_bf16_f32 %0, %1, %2" : "=v"(r) : "v"(lo), "v"(hi)); return r; }
; __device__ __forceinline__ float dpp_ror1(float x) { return __int_as_float(__builtin_amdgcn_update_dpp(0, __float_as_int(x), 0x121, 0xf, 0xf, false)); }
; __device__ __forceinline__ float dpp_ror2(float x) { return __int_as_float(__builtin_amdgcn_update_dpp(0, __float_as_int(x), 0x122, 0xf, 0xf, false)); }
;     __device__ __forceinline__ void operator()(const f32x4 (&acc)[2][2][4][2], const Unit& u, int wr, int wc, int fr, int fq) const {
;     ...
;                 for (int m = 0; m < 4; ++m) {
;                     f32x4 cur[2], h[2];
; #pragma unroll
;                     for (int bj = 0; bj < 2; ++bj) { cur[bj] = acc[ai][bj][m][n] * rs[ai][m]; f32x4 x1, x2;
; #pragma unroll
;                         for (int e = 0; e < 4; ++e) { const float c1 = dpp_ror1(cur[bj][e]), p1 = dpp_ror1(pg[bj][e]), c2 = dpp_ror2(cur[bj][e]), p2 = dpp_ror2(pg[bj][e]);
;                             x1[e] = fr >= 1 ? c1 : p1; x2[e] = fr >= 2 ? c2 : p2; }
;                         h[bj] = bb[bj] + w0[bj] * x2 + w1[bj] * x1 + w2[bj] * cur[bj]; }
;                     if (ai == 0 && wr == 0 && m == 0 && fr < 2) {
;                         *(f32x4*)(hc0 + (size_t)(u.pm * 2 + fr) * FF2 + gcol + 4 * n) = h[0]; *(f32x4*)(hc0 + (size_t)(u.pm * 2 + fr) * FF2 + FF + gcol + 4 * n) = h[1]; }
;                     f32x4 a;
; #pragma unroll
;                     for (int e = 0; e < 4; ++e) { const float g = h[0][e]; a[e] = g * __builtin_amdgcn_rcpf(1.0f + __builtin_amdgcn_exp2f(-1.4426950408889634f * g)) * h[1][e]; }
;                     const unsigned p0 = cvt_pk_bf16(a[0], a[1]), p1 = cvt_pk_bf16(a[2], a[3]);
;                     if (n == 0) { pk_lo[ai][m][0] = p0; pk_lo[ai][m][1] = p1; }
.Lp7_norawh:
	v_pk_fma_f32 v[220:221], v[136:137], v[116:117], v[140:141]
	v_pk_fma_f32 v[222:223], v[138:139], v[118:119], v[142:143]
	v_pk_fma_f32 v[224:225], v[152:153], v[112:113], v[156:157]
	v_pk_fma_f32 v[226:227], v[154:155], v[114:115], v[158:159]
	v_cndmask_b32_e64 v188, v116, v124, s[98:99]
	v_cndmask_b32_e64 v189, v117, v125, s[98:99]
	v_cndmask_b32_e64 v196, v118, v126, s[98:99]
	v_cndmask_b32_e64 v197, v119, v127, s[98:99]
	v_cndmask_b32_e64 v200, v112, v120, s[98:99]
	v_cndmask_b32_e64 v201, v113, v121, s[98:99]
	v_cndmask_b32_e64 v204, v114, v122, s[98:99]
	v_cndmask_b32_e64 v205, v115, v123, s[98:99]
	v_fmac_f32_dpp v220, v188, v132 row_ror:1 row_mask:0xf bank_mask:0xf
	v_fmac_f32_dpp v221, v189, v133 row_ror:1 row_mask:0xf bank_mask:0xf
	v_fmac_f32_dpp v222, v196, v134 row_ror:1 row_mask:0xf bank_mask:0xf
	v_fmac_f32_dpp v223, v197, v135 row_ror:1 row_mask:0xf bank_mask:0xf
	v_fmac_f32_dpp v224, v200, v148 row_ror:1 row_mask:0xf bank_mask:0xf
	v_fmac_f32_dpp v225, v201, v149 row_ror:1 row_mask:0xf bank_mask:0xf
	v_fmac_f32_dpp v226, v204, v150 row_ror:1 row_mask:0xf bank_mask:0xf
	v_fmac_f32_dpp v227, v205, v151 row_ror:1 row_mask:0xf bank_mask:0xf
	v_cndmask_b32_e64 v188, v124, v116, s[40:41]
	v_cndmask_b32_e64 v189, v125, v117, s[40:41]
	v_cndmask_b32_e64 v196, v126, v118, s[40:41]
	v_cndmask_b32_e64 v197, v127, v119, s[40:41]
	v_cndmask_b32_e64 v200, v120, v112, s[40:41]
	v_cndmask_b32_e64 v201, v121, v113, s[40:41]
	v_cndmask_b32_e64 v204, v122, v114, s[40:41]
	v_cndmask_b32_e64 v205, v123, v115, s[40:41]
	v_fmac_f32_dpp v220, v188, v128 row_ror:2 row_mask:0xf bank_mask:0xf
	v_fmac_f32_dpp v221, v189, v129 row_ror:2 row_mask:0xf bank_mask:0xf
	v_fmac_f32_dpp v222, v196, v130 row_ror:2 row_mask:0xf bank_mask:0xf
	v_fmac_f32_dpp v223, v197, v131 row_ror:2 row_mask:0xf bank_mask:0xf
	v_fmac_f32_dpp v224, v200, v144 row_ror:2 row_mask:0xf bank_mask:0xf
	v_fmac_f32_dpp v225, v201, v145 row_ror:2 row_mask:0xf bank_mask:0xf
	v_fmac_f32_dpp v226, v204, v146 row_ror:2 row_mask:0xf bank_mask:0xf
	v_fmac_f32_dpp v227, v205, v147 row_ror:2 row_mask:0xf bank_mask:0xf
	v_pk_mul_f32 v[190:191], v[220:221], s[100:101] op_sel_hi:[1,0]
	v_pk_mul_f32 v[250:251], v[222:223], s[100:101] op_sel_hi:[1,0]
	v_exp_f32_e32 v190, v190
	v_exp_f32_e32 v191, v191
	v_exp_f32_e32 v250, v250
	v_exp_f32_e32 v251, v251
	v_pk_mul_f32 v[220:221], v[220:221], v[224:225]
	v_pk_mul_f32 v[222:223], v[222:223], v[226:227]
	v_pk_add_f32 v[190:191], v[190:191], 1.0 op_sel_hi:[1,0]
	v_pk_add_f32 v[250:251], v[250:251], 1.0 op_sel_hi:[1,0]
	v_rcp_f32_e32 v190, v190
	v_rcp_f32_e32 v191, v191
	v_rcp_f32_e32 v250, v250
	v_rcp_f32_e32 v251, v251
	v_pk_mul_f32 v[220:221], v[220:221], v[190:191]
	v_pk_mul_f32 v[222:223], v[222:223], v[250:251]
	v_cvt_pk_bf16_f32 v194, v220, v221
	v_cvt_pk_bf16_f32 v195, v222, v223
	v_pk_fma_f32 v[220:221], v[136:137], v[108:109], v[140:141]
	v_pk_fma_f32 v[222:223], v[138:139], v[110:111], v[142:143]
	v_pk_fma_f32 v[224:225], v[152:153], v[104:105], v[156:157]
	v_pk_fma_f32 v[226:227], v[154:155], v[106:107], v[158:159]
	v_cndmask_b32_e64 v188, v108, v116, s[98:99]
	v_cndmask_b32_e64 v189, v109, v117, s[98:99]
	v_cndmask_b32_e64 v196, v110, v118, s[98:99]
	v_cndmask_b32_e64 v197, v111, v119, s[98:99]
	v_cndmask_b32_e64 v200, v104, v112, s[98:99]
	v_cndmask_b32_e64 v201, v105, v113, s[98:99]
	v_cndmask_b32_e64 v204, v106, v114, s[98:99]
	v_cndmask_b32_e64 v205, v107, v115, s[98:99]
	v_fmac_f32_dpp v220, v188, v132 row_ror:1 row_mask:0xf bank_mask:0xf
	v_fmac_f32_dpp v221, v189, v133 row_ror:1 row_mask:0xf bank_mask:0xf
	v_fmac_f32_dpp v222, v196, v134 row_ror:1 row_mask:0xf bank_mask:0xf
	v_fmac_f32_dpp v223, v197, v135 row_ror:1 row_mask:0xf bank_mask:0xf
	v_fmac_f32_dpp v224, v200, v148 row_ror:1 row_mask:0xf bank_mask:0xf
	v_fmac_f32_dpp v225, v201, v149 row_ror:1 row_mask:0xf bank_mask:0xf
	v_fmac_f32_dpp v226, v204, v150 row_ror:1 row_mask:0xf bank_mask:0xf
	v_fmac_f32_dpp v227, v205, v151 row_ror:1 row_mask:0xf bank_mask:0xf
	v_cndmask_b32_e64 v188, v116, v108, s[40:41]
	v_cndmask_b32_e64 v189, v117, v109, s[40:41]
	v_cndmask_b32_e64 v196, v118, v110, s[40:41]
	v_cndmask_b32_e64 v197, v119, v111, s[40:41]
	v_cndmask_b32_e64 v200, v112, v104, s[40:41]
	v_cndmask_b32_e64 v201, v113, v105, s[40:41]
	v_cndmask_b32_e64 v204, v114, v106, s[40:41]
	v_cndmask_b32_e64 v205, v115, v107, s[40:41]
	v_fmac_f32_dpp v220, v188, v128 row_ror:2 row_mask:0xf bank_mask:0xf
	v_fmac_f32_dpp v221, v189, v129 row_ror:2 row_mask:0xf bank_mask:0xf
	v_fmac_f32_dpp v222, v196, v130 row_ror:2 row_mask:0xf bank_mask:0xf
	v_fmac_f32_dpp v223, v197, v131 row_ror:2 row_mask:0xf bank_mask:0xf
	v_fmac_f32_dpp v224, v200, v144 row_ror:2 row_mask:0xf bank_mask:0xf
	v_fmac_f32_dpp v225, v201, v145 row_ror:2 row_mask:0xf bank_mask:0xf
	v_fmac_f32_dpp v226, v204, v146 row_ror:2 row_mask:0xf bank_mask:0xf
	v_fmac_f32_dpp v227, v205, v147 row_ror:2 row_mask:0xf bank_mask:0xf
	v_pk_mul_f32 v[190:191], v[220:221], s[100:101] op_sel_hi:[1,0]
	v_pk_mul_f32 v[250:251], v[222:223], s[100:101] op_sel_hi:[1,0]
	v_exp_f32_e32 v190, v190
	v_exp_f32_e32 v191, v191
	v_exp_f32_e32 v250, v250
	v_exp_f32_e32 v251, v251
	v_pk_mul_f32 v[220:221], v[220:221], v[224:225]
	v_pk_mul_f32 v[222:223], v[222:223], v[226:227]
	v_pk_add_f32 v[190:191], v[190:191], 1.0 op_sel_hi:[1,0]
	v_pk_add_f32 v[250:251], v[250:251], 1.0 op_sel_hi:[1,0]
	v_rcp_f32_e32 v190, v190
	v_rcp_f32_e32 v191, v191
	v_rcp_f32_e32 v250, v250
	v_rcp_f32_e32 v251, v251
	v_pk_mul_f32 v[220:221], v[220:221], v[190:191]
	v_pk_mul_f32 v[222:223], v[222:223], v[250:251]
	v_cvt_pk_bf16_f32 v198, v220, v221
	v_cvt_pk_bf16_f32 v199, v222, v223
; #define PG8_LAS __attribute__((address_space(3)))
; __device__ __forceinline__ float dpp_ror1(float x) { return __int_as_float(__builtin_amdgcn_update_dpp(0, __float_as_int(x), 0x121, 0xf, 0xf, false)); }
; __device__ __forceinline__ float dpp_ror2(float x) { return __int_as_float(__builtin_amdgcn_update_dpp(0, __float_as_int(x), 0x122, 0xf, 0xf, false)); }
;     __device__ __forceinline__ void operator()(const f32x4 (&acc)[2][2][4][2], const Unit& u, int wr, int wc, int fr, int fq) const {
;     ...
;             if (n == 1) {
; #pragma unroll
;                 for (int bj = 0; bj < 2; ++bj) { const int col = bj * FF + gcol + 4;
;                     w0[bj] = *(const f32x4*)(cw + col); w1[bj] = *(const f32x4*)(cw + FF2 + col); w2[bj] = *(const f32x4*)(cw + 2 * FF2 + col); bb[bj] = *(const f32x4*)(cb + col); } }
; #pragma unroll
;             for (int ai = 0; ai < 2; ++ai) {
;                 f32x4 pg[2]; const int pb = ai * 2 + wr - 1;
; #pragma unroll
;                 for (int bj = 0; bj < 2; ++bj) { pg[bj] = (f32x4){0.f, 0.f, 0.f, 0.f};
;                     if (pb >= 0 && fr >= 14) pg[bj] = *(const PG8_LAS f32x4*)(halo + (pb * 2 + (fr - 14)) * 256 + bj * HALF + lcol + 4 * n); }
; #pragma unroll
;                 for (int m = 0; m < 4; ++m) {
;                     f32x4 cur[2], h[2];
; #pragma unroll
;                     for (int bj = 0; bj < 2; ++bj) { cur[bj] = acc[ai][bj][m][n] * rs[ai][m]; f32x4 x1, x2;
; #pragma unroll
;                         for (int e = 0; e < 4; ++e) { const float c1 = dpp_ror1(cur[bj][e]), p1 = dpp_ror1(pg[bj][e]), c2 = dpp_ror2(cur[bj][e]), p2 = dpp_ror2(pg[bj][e]);
;                             x1[e] = fr >= 1 ? c1 : p1; x2[e] = fr >= 2 ? c2 : p2; }
;                         h[bj] = bb[bj] + w0[bj] * x2 + w1[bj] * x1 + w2[bj] * cur[bj]; }
;                     if (ai == 0 && wr == 0 && m == 0 && fr < 2) {
;                         *(f32x4*)(hc0 + (size_t)(u.pm * 2 + fr) * FF2 + gcol + 4 * n) = h[0]; *(f32x4*)(hc0 + (size_t)(u.pm * 2 + fr) * FF2 + FF + gcol + 4 * n) = h[1]; }
;                     f32x4 a;
; #pragma unroll
;                     for (int e = 0; e < 4; ++e) { const float g = h[0][e]; a[e] = g * __builtin_amdgcn_rcpf(1.0f + __builtin_amdgcn_exp2f(-1.4426950408889634f * g)) * h[1][e]; }
	v_pk_fma_f32 v[220:221], v[136:137], v[100:101], v[140:141]
	v_pk_fma_f32 v[222:223], v[138:139], v[102:103], v[142:143]
	v_pk_fma_f32 v[224:225], v[152:153], v[96:97], v[156:157]
	v_pk_fma_f32 v[226:227], v[154:155], v[98:99], v[158:159]
	v_cndmask_b32_e64 v188, v100, v108, s[98:99]
	v_cndmask_b32_e64 v189, v101, v109, s[98:99]
	v_cndmask_b32_e64 v196, v102, v110, s[98:99]
	v_cndmask_b32_e64 v197, v103, v111, s[98:99]
	v_cndmask_b32_e64 v200, v96, v104, s[98:99]
	v_cndmask_b32_e64 v201, v97, v105, s[98:99]
	v_cndmask_b32_e64 v204, v98, v106, s[98:99]
	v_cndmask_b32_e64 v205, v99, v107, s[98:99]
	v_fmac_f32_dpp v220, v188, v132 row_ror:1 row_mask:0xf bank_mask:0xf
	v_fmac_f32_dpp v221, v189, v133 row_ror:1 row_mask:0xf bank_mask:0xf
	v_fmac_f32_dpp v222, v196, v134 row_ror:1 row_mask:0xf bank_mask:0xf
	v_fmac_f32_dpp v223, v197, v135 row_ror:1 row_mask:0xf bank_mask:0xf
	v_fmac_f32_dpp v224, v200, v148 row_ror:1 row_mask:0xf bank_mask:0xf
	v_fmac_f32_dpp v225, v201, v149 row_ror:1 row_mask:0xf bank_mask:0xf
	v_fmac_f32_dpp v226, v204, v150 row_ror:1 row_mask:0xf bank_mask:0xf
	v_fmac_f32_dpp v227, v205, v151 row_ror:1 row_mask:0xf bank_mask:0xf
	v_cndmask_b32_e64 v188, v108, v100, s[40:41]
	v_cndmask_b32_e64 v189, v109, v101, s[40:41]
	v_cndmask_b32_e64 v196, v110, v102, s[40:41]
	v_cndmask_b32_e64 v197, v111, v103, s[40:41]
	v_cndmask_b32_e64 v200, v104, v96, s[40:41]
	v_cndmask_b32_e64 v201, v105, v97, s[40:41]
	v_cndmask_b32_e64 v204, v106, v98, s[40:41]
	v_cndmask_b32_e64 v205, v107, v99, s[40:41]
	v_fmac_f32_dpp v220, v188, v128 row_ror:2 row_mask:0xf bank_mask:0xf
	v_fmac_f32_dpp v221, v189, v129 row_ror:2 row_mask:0xf bank_mask:0xf
	v_fmac_f32_dpp v222, v196, v130 row_ror:2 row_mask:0xf bank_mask:0xf
	v_fmac_f32_dpp v223, v197, v131 row_ror:2 row_mask:0xf bank_mask:0xf
	v_fmac_f32_dpp v224, v200, v144 row_ror:2 row_mask:0xf bank_mask:0xf
	v_fmac_f32_dpp v225, v201, v145 row_ror:2 row_mask:0xf bank_mask:0xf
	v_fmac_f32_dpp v226, v204, v146 row_ror:2 row_mask:0xf bank_mask:0xf
	v_fmac_f32_dpp v227, v205, v147 row_ror:2 row_mask:0xf bank_mask:0xf
	v_pk_mul_f32 v[190:191], v[220:221], s[100:101] op_sel_hi:[1,0]
	v_pk_mul_f32 v[250:251], v[222:223], s[100:101] op_sel_hi:[1,0]
	v_exp_f32_e32 v190, v190
	v_exp_f32_e32 v191, v191
	v_exp_f32_e32 v250, v250
	v_exp_f32_e32 v251, v251
	v_pk_mul_f32 v[220:221], v[220:221], v[224:225]
	v_pk_mul_f32 v[222:223], v[222:223], v[226:227]
	v_pk_add_f32 v[190:191], v[190:191], 1.0 op_sel_hi:[1,0]
	v_pk_add_f32 v[250:251], v[250:251], 1.0 op_sel_hi:[1,0]
	v_rcp_f32_e32 v190, v190
	v_rcp_f32_e32 v191, v191
	v_rcp_f32_e32 v250, v250
	v_rcp_f32_e32 v251, v251
	v_pk_mul_f32 v[220:221], v[220:221], v[190:191]
	v_pk_mul_f32 v[222:223], v[222:223], v[250:251]
	v_cvt_pk_bf16_f32 v202, v220, v221
	v_cvt_pk_bf16_f32 v203, v222, v223
	ds_read_b128 v[124:127], v235 offset:16
	ds_read_b128 v[116:119], v235 offset:1040
	ds_read_b128 v[108:111], v235 offset:2064
	ds_read_b128 v[100:103], v235 offset:3088
	ds_read_b128 v[120:123], v235 offset:528
	ds_read_b128 v[112:115], v235 offset:1552
	ds_read_b128 v[104:107], v235 offset:2576
	ds_read_b128 v[96:99], v235 offset:3600
	v_pk_fma_f32 v[220:221], v[136:137], v[92:93], v[140:141]
	v_pk_fma_f32 v[222:223], v[138:139], v[94:95], v[142:143]
	v_pk_fma_f32 v[224:225], v[152:153], v[88:89], v[156:157]
	v_pk_fma_f32 v[226:227], v[154:155], v[90:91], v[158:159]
	v_cndmask_b32_e64 v188, v92, v178, s[98:99]
	v_cndmask_b32_e64 v189, v93, v179, s[98:99]
	v_cndmask_b32_e64 v196, v94, v180, s[98:99]
	v_cndmask_b32_e64 v197, v95, v181, s[98:99]
	v_cndmask_b32_e64 v200, v88, v182, s[98:99]
	v_cndmask_b32_e64 v201, v89, v183, s[98:99]
	v_cndmask_b32_e64 v204, v90, v184, s[98:99]
	v_cndmask_b32_e64 v205, v91, v185, s[98:99]
	v_fmac_f32_dpp v220, v188, v132 row_ror:1 row_mask:0xf bank_mask:0xf
	v_fmac_f32_dpp v221, v189, v133 row_ror:1 row_mask:0xf bank_mask:0xf
	v_fmac_f32_dpp v222, v196, v134 row_ror:1 row_mask:0xf bank_mask:0xf
	v_fmac_f32_dpp v223, v197, v135 row_ror:1 row_mask:0xf bank_mask:0xf
	v_fmac_f32_dpp v224, v200, v148 row_ror:1 row_mask:0xf bank_mask:0xf
	v_fmac_f32_dpp v225, v201, v149 row_ror:1 row_mask:0xf bank_mask:0xf
	v_fmac_f32_dpp v226, v204, v150 row_ror:1 row_mask:0xf bank_mask:0xf
	v_fmac_f32_dpp v227, v205, v151 row_ror:1 row_mask:0xf bank_mask:0xf
	v_cndmask_b32_e64 v188, v178, v92, s[40:41]
	v_cndmask_b32_e64 v189, v179, v93, s[40:41]
	v_cndmask_b32_e64 v196, v180, v94, s[40:41]
	v_cndmask_b32_e64 v197, v181, v95, s[40:41]
	v_cndmask_b32_e64 v200, v182, v88, s[40:41]
	v_cndmask_b32_e64 v201, v183, v89, s[40:41]
	v_cndmask_b32_e64 v204, v184, v90, s[40:41]
	v_cndmask_b32_e64 v205, v185, v91, s[40:41]
	v_fmac_f32_dpp v220, v188, v128 row_ror:2 row_mask:0xf bank_mask:0xf
	v_fmac_f32_dpp v221, v189, v129 row_ror:2 row_mask:0xf bank_mask:0xf
	v_fmac_f32_dpp v222, v196, v130 row_ror:2 row_mask:0xf bank_mask:0xf
	v_fmac_f32_dpp v223, v197, v131 row_ror:2 row_mask:0xf bank_mask:0xf
	v_fmac_f32_dpp v224, v200, v144 row_ror:2 row_mask:0xf bank_mask:0xf
	v_fmac_f32_dpp v225, v201, v145 row_ror:2 row_mask:0xf bank_mask:0xf
	v_fmac_f32_dpp v226, v204, v146 row_ror:2 row_mask:0xf bank_mask:0xf
	v_fmac_f32_dpp v227, v205, v147 row_ror:2 row_mask:0xf bank_mask:0xf
	v_pk_mul_f32 v[190:191], v[220:221], s[100:101] op_sel_hi:[1,0]
	v_pk_mul_f32 v[250:251], v[222:223], s[100:101] op_sel_hi:[1,0]
	v_exp_f32_e32 v190, v190
	v_exp_f32_e32 v191, v191
	v_exp_f32_e32 v250, v250
	v_exp_f32_e32 v251, v251
	v_pk_mul_f32 v[220:221], v[220:221], v[224:225]
	v_pk_mul_f32 v[222:223], v[222:223], v[226:227]
	v_pk_add_f32 v[190:191], v[190:191], 1.0 op_sel_hi:[1,0]
; #define PG8_LAS __attribute__((address_space(3)))
; __device__ __forceinline__ unsigned cvt_pk_bf16(float lo, float hi) { unsigned r; asm volatile("v_cvt_pk_bf16_f32 %0, %1, %2" : "=v"(r) : "v"(lo), "v"(hi)); return r; }
; __device__ __forceinline__ float dpp_ror1(float x) { return __int_as_float(__builtin_amdgcn_update_dpp(0, __float_as_int(x), 0x121, 0xf, 0xf, false)); }
;     __device__ __forceinline__ void operator()(const f32x4 (&acc)[2][2][4][2], const Unit& u, int wr, int wc, int fr, int fq) const {
;     ...
;             for (int ai = 0; ai < 2; ++ai) {
;                 f32x4 pg[2]; const int pb = ai * 2 + wr - 1;
; #pragma unroll
;                 for (int bj = 0; bj < 2; ++bj) { pg[bj] = (f32x4){0.f, 0.f, 0.f, 0.f};
;                     if (pb >= 0 && fr >= 14) pg[bj] = *(const PG8_LAS f32x4*)(halo + (pb * 2 + (fr - 14)) * 256 + bj * HALF + lcol + 4 * n); }
; #pragma unroll
;                 for (int m = 0; m < 4; ++m) {
;                     f32x4 cur[2], h[2];
; #pragma unroll
;                     for (int bj = 0; bj < 2; ++bj) { cur[bj] = acc[ai][bj][m][n] * rs[ai][m]; f32x4 x1, x2;
; #pragma unroll
;                         for (int e = 0; e < 4; ++e) { const float c1 = dpp_ror1(cur[bj][e]), p1 = dpp_ror1(pg[bj][e]), c2 = dpp_ror2(cur[bj][e]), p2 = dpp_ror2(pg[bj][e]);
;                             x1[e] = fr >= 1 ? c1 : p1; x2[e] = fr >= 2 ? c2 : p2; }
;                         h[bj] = bb[bj] + w0[bj] * x2 + w1[bj] * x1 + w2[bj] * cur[bj]; }
;                     if (ai == 0 && wr == 0 && m == 0 && fr < 2) {
;                         *(f32x4*)(hc0 + (size_t)(u.pm * 2 + fr) * FF2 + gcol + 4 * n) = h[0]; *(f32x4*)(hc0 + (size_t)(u.pm * 2 + fr) * FF2 + FF + gcol + 4 * n) = h[1]; }
;                     f32x4 a;
; #pragma unroll
;                     for (int e = 0; e < 4; ++e) { const float g = h[0][e]; a[e] = g * __builtin_amdgcn_rcpf(1.0f + __builtin_amdgcn_exp2f(-1.4426950408889634f * g)) * h[1][e]; }
;                     const unsigned p0 = cvt_pk_bf16(a[0], a[1]), p1 = cvt_pk_bf16(a[2], a[3]);
;                     if (n == 0) { pk_lo[ai][m][0] = p0; pk_lo[ai][m][1] = p1; }
;                     else { u32x4 w; w.x = pk_lo[ai][m][0]; w.y = pk_lo[ai][m][1]; w.z = p0; w.w = p1;
;                         *(u32x4*)(act + (size_t)(u.pm * BM + ai * HALF + wr * 64 + m * 16 + fr) * FF + gcol) = w; }
	v_pk_add_f32 v[250:251], v[250:251], 1.0 op_sel_hi:[1,0]
	v_rcp_f32_e32 v190, v190
	v_rcp_f32_e32 v191, v191
	v_rcp_f32_e32 v250, v250
	v_rcp_f32_e32 v251, v251
	v_pk_mul_f32 v[220:221], v[220:221], v[190:191]
	v_pk_mul_f32 v[222:223], v[222:223], v[250:251]
	v_cvt_pk_bf16_f32 v160, v220, v221
	v_cvt_pk_bf16_f32 v161, v222, v223
	v_pk_fma_f32 v[220:221], v[136:137], v[84:85], v[140:141]
	v_pk_fma_f32 v[222:223], v[138:139], v[86:87], v[142:143]
	v_pk_fma_f32 v[224:225], v[152:153], v[80:81], v[156:157]
	v_pk_fma_f32 v[226:227], v[154:155], v[82:83], v[158:159]
	v_cndmask_b32_e64 v188, v84, v92, s[98:99]
	v_cndmask_b32_e64 v189, v85, v93, s[98:99]
	v_cndmask_b32_e64 v196, v86, v94, s[98:99]
	v_cndmask_b32_e64 v197, v87, v95, s[98:99]
	v_cndmask_b32_e64 v200, v80, v88, s[98:99]
	v_cndmask_b32_e64 v201, v81, v89, s[98:99]
	v_cndmask_b32_e64 v204, v82, v90, s[98:99]
	v_cndmask_b32_e64 v205, v83, v91, s[98:99]
	v_fmac_f32_dpp v220, v188, v132 row_ror:1 row_mask:0xf bank_mask:0xf
	v_fmac_f32_dpp v221, v189, v133 row_ror:1 row_mask:0xf bank_mask:0xf
	v_fmac_f32_dpp v222, v196, v134 row_ror:1 row_mask:0xf bank_mask:0xf
	v_fmac_f32_dpp v223, v197, v135 row_ror:1 row_mask:0xf bank_mask:0xf
	v_fmac_f32_dpp v224, v200, v148 row_ror:1 row_mask:0xf bank_mask:0xf
	v_fmac_f32_dpp v225, v201, v149 row_ror:1 row_mask:0xf bank_mask:0xf
	v_fmac_f32_dpp v226, v204, v150 row_ror:1 row_mask:0xf bank_mask:0xf
	v_fmac_f32_dpp v227, v205, v151 row_ror:1 row_mask:0xf bank_mask:0xf
	v_cndmask_b32_e64 v188, v92, v84, s[40:41]
	v_cndmask_b32_e64 v189, v93, v85, s[40:41]
	v_cndmask_b32_e64 v196, v94, v86, s[40:41]
	v_cndmask_b32_e64 v197, v95, v87, s[40:41]
	v_cndmask_b32_e64 v200, v88, v80, s[40:41]
	v_cndmask_b32_e64 v201, v89, v81, s[40:41]
	v_cndmask_b32_e64 v204, v90, v82, s[40:41]
	v_cndmask_b32_e64 v205, v91, v83, s[40:41]
	v_fmac_f32_dpp v220, v188, v128 row_ror:2 row_mask:0xf bank_mask:0xf
	v_fmac_f32_dpp v221, v189, v129 row_ror:2 row_mask:0xf bank_mask:0xf
	v_fmac_f32_dpp v222, v196, v130 row_ror:2 row_mask:0xf bank_mask:0xf
	v_fmac_f32_dpp v223, v197, v131 row_ror:2 row_mask:0xf bank_mask:0xf
	v_fmac_f32_dpp v224, v200, v144 row_ror:2 row_mask:0xf bank_mask:0xf
	v_fmac_f32_dpp v225, v201, v145 row_ror:2 row_mask:0xf bank_mask:0xf
	v_fmac_f32_dpp v226, v204, v146 row_ror:2 row_mask:0xf bank_mask:0xf
	v_fmac_f32_dpp v227, v205, v147 row_ror:2 row_mask:0xf bank_mask:0xf
	v_pk_mul_f32 v[190:191], v[220:221], s[100:101] op_sel_hi:[1,0]
	v_pk_mul_f32 v[250:251], v[222:223], s[100:101] op_sel_hi:[1,0]
	v_exp_f32_e32 v190, v190
	v_exp_f32_e32 v191, v191
	v_exp_f32_e32 v250, v250
	v_exp_f32_e32 v251, v251
	v_pk_mul_f32 v[220:221], v[220:221], v[224:225]
	v_pk_mul_f32 v[222:223], v[222:223], v[226:227]
	v_pk_add_f32 v[190:191], v[190:191], 1.0 op_sel_hi:[1,0]
	v_pk_add_f32 v[250:251], v[250:251], 1.0 op_sel_hi:[1,0]
	v_rcp_f32_e32 v190, v190
	v_rcp_f32_e32 v191, v191
	v_rcp_f32_e32 v250, v250
	v_rcp_f32_e32 v251, v251
	v_pk_mul_f32 v[220:221], v[220:221], v[190:191]
	v_pk_mul_f32 v[222:223], v[222:223], v[250:251]
	v_cvt_pk_bf16_f32 v164, v220, v221
	v_cvt_pk_bf16_f32 v165, v222, v223
	v_pk_fma_f32 v[220:221], v[136:137], v[76:77], v[140:141]
	v_pk_fma_f32 v[222:223], v[138:139], v[78:79], v[142:143]
	v_pk_fma_f32 v[224:225], v[152:153], v[72:73], v[156:157]
	v_pk_fma_f32 v[226:227], v[154:155], v[74:75], v[158:159]
	v_cndmask_b32_e64 v188, v76, v84, s[98:99]
	v_cndmask_b32_e64 v189, v77, v85, s[98:99]
	v_cndmask_b32_e64 v196, v78, v86, s[98:99]
	v_cndmask_b32_e64 v197, v79, v87, s[98:99]
	v_cndmask_b32_e64 v200, v72, v80, s[98:99]
	v_cndmask_b32_e64 v201, v73, v81, s[98:99]
	v_cndmask_b32_e64 v204, v74, v82, s[98:99]
	v_cndmask_b32_e64 v205, v75, v83, s[98:99]
	v_fmac_f32_dpp v220, v188, v132 row_ror:1 row_mask:0xf bank_mask:0xf
	v_fmac_f32_dpp v221, v189, v133 row_ror:1 row_mask:0xf bank_mask:0xf
	v_fmac_f32_dpp v222, v196, v134 row_ror:1 row_mask:0xf bank_mask:0xf
	v_fmac_f32_dpp v223, v197, v135 row_ror:1 row_mask:0xf bank_mask:0xf
	v_fmac_f32_dpp v224, v200, v148 row_ror:1 row_mask:0xf bank_mask:0xf
	v_fmac_f32_dpp v225, v201, v149 row_ror:1 row_mask:0xf bank_mask:0xf
	v_fmac_f32_dpp v226, v204, v150 row_ror:1 row_mask:0xf bank_mask:0xf
	v_fmac_f32_dpp v227, v205, v151 row_ror:1 row_mask:0xf bank_mask:0xf
	v_cndmask_b32_e64 v188, v84, v76, s[40:41]
	v_cndmask_b32_e64 v189, v85, v77, s[40:41]
	v_cndmask_b32_e64 v196, v86, v78, s[40:41]
	v_cndmask_b32_e64 v197, v87, v79, s[40:41]
	v_cndmask_b32_e64 v200, v80, v72, s[40:41]
	v_cndmask_b32_e64 v201, v81, v73, s[40:41]
	v_cndmask_b32_e64 v204, v82, v74, s[40:41]
	v_cndmask_b32_e64 v205, v83, v75, s[40:41]
	v_fmac_f32_dpp v220, v188, v128 row_ror:2 row_mask:0xf bank_mask:0xf
	v_fmac_f32_dpp v221, v189, v129 row_ror:2 row_mask:0xf bank_mask:0xf
	v_fmac_f32_dpp v222, v196, v130 row_ror:2 row_mask:0xf bank_mask:0xf
	v_fmac_f32_dpp v223, v197, v131 row_ror:2 row_mask:0xf bank_mask:0xf
	v_fmac_f32_dpp v224, v200, v144 row_ror:2 row_mask:0xf bank_mask:0xf
	v_fmac_f32_dpp v225, v201, v145 row_ror:2 row_mask:0xf bank_mask:0xf
	v_fmac_f32_dpp v226, v204, v146 row_ror:2 row_mask:0xf bank_mask:0xf
	v_fmac_f32_dpp v227, v205, v147 row_ror:2 row_mask:0xf bank_mask:0xf
	v_pk_mul_f32 v[190:191], v[220:221], s[100:101] op_sel_hi:[1,0]
	v_pk_mul_f32 v[250:251], v[222:223], s[100:101] op_sel_hi:[1,0]
	v_exp_f32_e32 v190, v190
	v_exp_f32_e32 v191, v191
	v_exp_f32_e32 v250, v250
	v_exp_f32_e32 v251, v251
	v_pk_mul_f32 v[220:221], v[220:221], v[224:225]
	v_pk_mul_f32 v[222:223], v[222:223], v[226:227]
	v_pk_add_f32 v[190:191], v[190:191], 1.0 op_sel_hi:[1,0]
	v_pk_add_f32 v[250:251], v[250:251], 1.0 op_sel_hi:[1,0]
	v_rcp_f32_e32 v190, v190
	v_rcp_f32_e32 v191, v191
	v_rcp_f32_e32 v250, v250
	v_rcp_f32_e32 v251, v251
	v_pk_mul_f32 v[220:221], v[220:221], v[190:191]
	v_pk_mul_f32 v[222:223], v[222:223], v[250:251]
	v_cvt_pk_bf16_f32 v178, v220, v221
	v_cvt_pk_bf16_f32 v179, v222, v223
	s_and_b64 vcc, exec, s[94:95]
	s_cbranch_vccnz .Lp7_hz1
	ds_read_b128 v[92:95], v215
	ds_read_b128 v[88:91], v216
	s_branch .Lp7_hr1

; #define PG8_LAS __attribute__((address_space(3)))
; __device__ __forceinline__ unsigned cvt_pk_bf16(float lo, float hi) { unsigned r; asm volatile("v_cvt_pk_bf16_f32 %0, %1, %2" : "=v"(r) : "v"(lo), "v"(hi)); return r; }
; __device__ __forceinline__ float dpp_ror1(float x) { return __int_as_float(__builtin_amdgcn_update_dpp(0, __float_as_int(x), 0x121, 0xf, 0xf, false)); }
; __device__ __forceinline__ float dpp_ror2(float x) { return __int_as_float(__builtin_amdgcn_update_dpp(0, __float_as_int(x), 0x122, 0xf, 0xf, false)); }
;     __device__ __forceinline__ void operator()(const f32x4 (&acc)[2][2][4][2], const Unit& u, int wr, int wc, int fr, int fq) const {
;     ...
;                     if (pb >= 0 && fr >= 14) pg[bj] = *(const PG8_LAS f32x4*)(halo + (pb * 2 + (fr - 14)) * 256 + bj * HALF + lcol + 4 * n); }
; #pragma unroll
;                 for (int m = 0; m < 4; ++m) {
;                     f32x4 cur[2], h[2];
; #pragma unroll
;                     for (int bj = 0; bj < 2; ++bj) { cur[bj] = acc[ai][bj][m][n] * rs[ai][m]; f32x4 x1, x2;
; #pragma unroll
;                         for (int e = 0; e < 4; ++e) { const float c1 = dpp_ror1(cur[bj][e]), p1 = dpp_ror1(pg[bj][e]), c2 = dpp_ror2(cur[bj][e]), p2 = dpp_ror2(pg[bj][e]);
;                             x1[e] = fr >= 1 ? c1 : p1; x2[e] = fr >= 2 ? c2 : p2; }
;                         h[bj] = bb[bj] + w0[bj] * x2 + w1[bj] * x1 + w2[bj] * cur[bj]; }
;                     if (ai == 0 && wr == 0 && m == 0 && fr < 2) {
;                         *(f32x4*)(hc0 + (size_t)(u.pm * 2 + fr) * FF2 + gcol + 4 * n) = h[0]; *(f32x4*)(hc0 + (size_t)(u.pm * 2 + fr) * FF2 + FF + gcol + 4 * n) = h[1]; }
;                     f32x4 a;
; #pragma unroll
;                     for (int e = 0; e < 4; ++e) { const float g = h[0][e]; a[e] = g * __builtin_amdgcn_rcpf(1.0f + __builtin_amdgcn_exp2f(-1.4426950408889634f * g)) * h[1][e]; }
;                     const unsigned p0 = cvt_pk_bf16(a[0], a[1]), p1 = cvt_pk_bf16(a[2], a[3]);
;                     if (n == 0) { pk_lo[ai][m][0] = p0; pk_lo[ai][m][1] = p1; }
;                     else { u32x4 w; w.x = pk_lo[ai][m][0]; w.y = pk_lo[ai][m][1]; w.z = p0; w.w = p1;
;                         *(u32x4*)(act + (size_t)(u.pm * BM + ai * HALF + wr * 64 + m * 16 + fr) * FF + gcol) = w; }
.Lp7_hr1:
	ds_read_b128 v[84:87], v217
	ds_read_b128 v[80:83], v218
	v_pk_fma_f32 v[220:221], v[136:137], v[68:69], v[140:141]
	v_pk_fma_f32 v[222:223], v[138:139], v[70:71], v[142:143]
	v_pk_fma_f32 v[224:225], v[152:153], v[64:65], v[156:157]
	v_pk_fma_f32 v[226:227], v[154:155], v[66:67], v[158:159]
	v_cndmask_b32_e64 v188, v68, v76, s[98:99]
	v_cndmask_b32_e64 v189, v69, v77, s[98:99]
	v_cndmask_b32_e64 v196, v70, v78, s[98:99]
	v_cndmask_b32_e64 v197, v71, v79, s[98:99]
	v_cndmask_b32_e64 v200, v64, v72, s[98:99]
	v_cndmask_b32_e64 v201, v65, v73, s[98:99]
	v_cndmask_b32_e64 v204, v66, v74, s[98:99]
	v_cndmask_b32_e64 v205, v67, v75, s[98:99]
	v_fmac_f32_dpp v220, v188, v132 row_ror:1 row_mask:0xf bank_mask:0xf
	v_fmac_f32_dpp v221, v189, v133 row_ror:1 row_mask:0xf bank_mask:0xf
	v_fmac_f32_dpp v222, v196, v134 row_ror:1 row_mask:0xf bank_mask:0xf
	v_fmac_f32_dpp v223, v197, v135 row_ror:1 row_mask:0xf bank_mask:0xf
	v_fmac_f32_dpp v224, v200, v148 row_ror:1 row_mask:0xf bank_mask:0xf
	v_fmac_f32_dpp v225, v201, v149 row_ror:1 row_mask:0xf bank_mask:0xf
	v_fmac_f32_dpp v226, v204, v150 row_ror:1 row_mask:0xf bank_mask:0xf
	v_fmac_f32_dpp v227, v205, v151 row_ror:1 row_mask:0xf bank_mask:0xf
	v_cndmask_b32_e64 v188, v76, v68, s[40:41]
	v_cndmask_b32_e64 v189, v77, v69, s[40:41]
	v_cndmask_b32_e64 v196, v78, v70, s[40:41]
	v_cndmask_b32_e64 v197, v79, v71, s[40:41]
	v_cndmask_b32_e64 v200, v72, v64, s[40:41]
	v_cndmask_b32_e64 v201, v73, v65, s[40:41]
	v_cndmask_b32_e64 v204, v74, v66, s[40:41]
	v_cndmask_b32_e64 v205, v75, v67, s[40:41]
	v_fmac_f32_dpp v220, v188, v128 row_ror:2 row_mask:0xf bank_mask:0xf
	v_fmac_f32_dpp v221, v189, v129 row_ror:2 row_mask:0xf bank_mask:0xf
	v_fmac_f32_dpp v222, v196, v130 row_ror:2 row_mask:0xf bank_mask:0xf
	v_fmac_f32_dpp v223, v197, v131 row_ror:2 row_mask:0xf bank_mask:0xf
	v_fmac_f32_dpp v224, v200, v144 row_ror:2 row_mask:0xf bank_mask:0xf
	v_fmac_f32_dpp v225, v201, v145 row_ror:2 row_mask:0xf bank_mask:0xf
	v_fmac_f32_dpp v226, v204, v146 row_ror:2 row_mask:0xf bank_mask:0xf
	v_fmac_f32_dpp v227, v205, v147 row_ror:2 row_mask:0xf bank_mask:0xf
	v_pk_mul_f32 v[190:191], v[220:221], s[100:101] op_sel_hi:[1,0]
	v_pk_mul_f32 v[250:251], v[222:223], s[100:101] op_sel_hi:[1,0]
	v_exp_f32_e32 v190, v190
	v_exp_f32_e32 v191, v191
	v_exp_f32_e32 v250, v250
	v_exp_f32_e32 v251, v251
	v_pk_mul_f32 v[220:221], v[220:221], v[224:225]
	v_pk_mul_f32 v[222:223], v[222:223], v[226:227]
	v_pk_add_f32 v[190:191], v[190:191], 1.0 op_sel_hi:[1,0]
	v_pk_add_f32 v[250:251], v[250:251], 1.0 op_sel_hi:[1,0]
	v_rcp_f32_e32 v190, v190
	v_rcp_f32_e32 v191, v191
	v_rcp_f32_e32 v250, v250
	v_rcp_f32_e32 v251, v251
	v_pk_mul_f32 v[220:221], v[220:221], v[190:191]
	v_pk_mul_f32 v[222:223], v[222:223], v[250:251]
	v_cvt_pk_bf16_f32 v182, v220, v221
	v_cvt_pk_bf16_f32 v183, v222, v223
	s_waitcnt lgkmcnt(0)
	v_pk_fma_f32 v[220:221], v[108:109], v[60:61], v[100:101]
	v_pk_fma_f32 v[222:223], v[110:111], v[62:63], v[102:103]
	v_pk_fma_f32 v[224:225], v[104:105], v[56:57], v[96:97]
	v_pk_fma_f32 v[226:227], v[106:107], v[58:59], v[98:99]
	v_cndmask_b32_e64 v72, v60, v92, s[98:99]
	v_cndmask_b32_e64 v73, v61, v93, s[98:99]
	v_cndmask_b32_e64 v74, v62, v94, s[98:99]
	v_cndmask_b32_e64 v75, v63, v95, s[98:99]
	v_cndmask_b32_e64 v76, v56, v88, s[98:99]
	v_cndmask_b32_e64 v77, v57, v89, s[98:99]
	v_cndmask_b32_e64 v78, v58, v90, s[98:99]
	v_cndmask_b32_e64 v79, v59, v91, s[98:99]
	v_fmac_f32_dpp v220, v72, v116 row_ror:1 row_mask:0xf bank_mask:0xf
	v_fmac_f32_dpp v221, v73, v117 row_ror:1 row_mask:0xf bank_mask:0xf
	v_fmac_f32_dpp v222, v74, v118 row_ror:1 row_mask:0xf bank_mask:0xf
	v_fmac_f32_dpp v223, v75, v119 row_ror:1 row_mask:0xf bank_mask:0xf
	v_fmac_f32_dpp v224, v76, v112 row_ror:1 row_mask:0xf bank_mask:0xf
	v_fmac_f32_dpp v225, v77, v113 row_ror:1 row_mask:0xf bank_mask:0xf
	v_fmac_f32_dpp v226, v78, v114 row_ror:1 row_mask:0xf bank_mask:0xf
	v_fmac_f32_dpp v227, v79, v115 row_ror:1 row_mask:0xf bank_mask:0xf
	v_cndmask_b32_e64 v72, v92, v60, s[40:41]
	v_cndmask_b32_e64 v73, v93, v61, s[40:41]
	v_cndmask_b32_e64 v74, v94, v62, s[40:41]
	v_cndmask_b32_e64 v75, v95, v63, s[40:41]
	v_cndmask_b32_e64 v76, v88, v56, s[40:41]
	v_cndmask_b32_e64 v77, v89, v57, s[40:41]
	v_cndmask_b32_e64 v78, v90, v58, s[40:41]
	v_cndmask_b32_e64 v79, v91, v59, s[40:41]
	v_fmac_f32_dpp v220, v72, v124 row_ror:2 row_mask:0xf bank_mask:0xf
	v_fmac_f32_dpp v221, v73, v125 row_ror:2 row_mask:0xf bank_mask:0xf
	v_fmac_f32_dpp v222, v74, v126 row_ror:2 row_mask:0xf bank_mask:0xf
	v_fmac_f32_dpp v223, v75, v127 row_ror:2 row_mask:0xf bank_mask:0xf
	v_fmac_f32_dpp v224, v76, v120 row_ror:2 row_mask:0xf bank_mask:0xf
	v_fmac_f32_dpp v225, v77, v121 row_ror:2 row_mask:0xf bank_mask:0xf
	v_fmac_f32_dpp v226, v78, v122 row_ror:2 row_mask:0xf bank_mask:0xf
	v_fmac_f32_dpp v227, v79, v123 row_ror:2 row_mask:0xf bank_mask:0xf
	s_and_saveexec_b64 s[0:1], s[12:13]
	global_store_dwordx4 v241, v[220:223], s[84:85] offset:16
	global_store_dwordx4 v249, v[224:227], s[84:85] offset:16
	s_or_b64 exec, exec, s[0:1]
	v_pk_mul_f32 v[190:191], v[220:221], s[100:101] op_sel_hi:[1,0]
	v_pk_mul_f32 v[250:251], v[222:223], s[100:101] op_sel_hi:[1,0]
	v_exp_f32_e32 v190, v190
	v_exp_f32_e32 v191, v191
	v_exp_f32_e32 v250, v250
	v_exp_f32_e32 v251, v251
	v_pk_mul_f32 v[220:221], v[220:221], v[224:225]
	v_pk_mul_f32 v[222:223], v[222:223], v[226:227]
	v_pk_add_f32 v[190:191], v[190:191], 1.0 op_sel_hi:[1,0]
	v_pk_add_f32 v[250:251], v[250:251], 1.0 op_sel_hi:[1,0]
	v_rcp_f32_e32 v190, v190
	v_rcp_f32_e32 v191, v191
	v_rcp_f32_e32 v250, v250
	v_rcp_f32_e32 v251, v251
; __device__ __forceinline__ unsigned cvt_pk_bf16(float lo, float hi) { unsigned r; asm volatile("v_cvt_pk_bf16_f32 %0, %1, %2" : "=v"(r) : "v"(lo), "v"(hi)); return r; }
; __device__ __forceinline__ float dpp_ror1(float x) { return __int_as_float(__builtin_amdgcn_update_dpp(0, __float_as_int(x), 0x121, 0xf, 0xf, false)); }
; __device__ __forceinline__ float dpp_ror2(float x) { return __int_as_float(__builtin_amdgcn_update_dpp(0, __float_as_int(x), 0x122, 0xf, 0xf, false)); }
;     __device__ __forceinline__ void operator()(const f32x4 (&acc)[2][2][4][2], const Unit& u, int wr, int wc, int fr, int fq) const {
;     ...
;                 for (int m = 0; m < 4; ++m) {
;                     f32x4 cur[2], h[2];
; #pragma unroll
;                     for (int bj = 0; bj < 2; ++bj) { cur[bj] = acc[ai][bj][m][n] * rs[ai][m]; f32x4 x1, x2;
; #pragma unroll
;                         for (int e = 0; e < 4; ++e) { const float c1 = dpp_ror1(cur[bj][e]), p1 = dpp_ror1(pg[bj][e]), c2 = dpp_ror2(cur[bj][e]), p2 = dpp_ror2(pg[bj][e]);
;                             x1[e] = fr >= 1 ? c1 : p1; x2[e] = fr >= 2 ? c2 : p2; }
;                         h[bj] = bb[bj] + w0[bj] * x2 + w1[bj] * x1 + w2[bj] * cur[bj]; }
;                     if (ai == 0 && wr == 0 && m == 0 && fr < 2) {
;                         *(f32x4*)(hc0 + (size_t)(u.pm * 2 + fr) * FF2 + gcol + 4 * n) = h[0]; *(f32x4*)(hc0 + (size_t)(u.pm * 2 + fr) * FF2 + FF + gcol + 4 * n) = h[1]; }
;                     f32x4 a;
; #pragma unroll
;                     for (int e = 0; e < 4; ++e) { const float g = h[0][e]; a[e] = g * __builtin_amdgcn_rcpf(1.0f + __builtin_amdgcn_exp2f(-1.4426950408889634f * g)) * h[1][e]; }
;                     const unsigned p0 = cvt_pk_bf16(a[0], a[1]), p1 = cvt_pk_bf16(a[2], a[3]);
;                     if (n == 0) { pk_lo[ai][m][0] = p0; pk_lo[ai][m][1] = p1; }
;                     else { u32x4 w; w.x = pk_lo[ai][m][0]; w.y = pk_lo[ai][m][1]; w.z = p0; w.w = p1;
;                         *(u32x4*)(act + (size_t)(u.pm * BM + ai * HALF + wr * 64 + m * 16 + fr) * FF + gcol) = w; }
	v_pk_mul_f32 v[220:221], v[220:221], v[190:191]
	v_pk_mul_f32 v[222:223], v[222:223], v[250:251]
	v_cvt_pk_bf16_f32 v188, v220, v221
	v_cvt_pk_bf16_f32 v189, v222, v223
	global_store_dwordx4 v239, v[186:189], s[24:25]
	v_pk_fma_f32 v[220:221], v[108:109], v[52:53], v[100:101]
	v_pk_fma_f32 v[222:223], v[110:111], v[54:55], v[102:103]
	v_pk_fma_f32 v[224:225], v[104:105], v[48:49], v[96:97]
	v_pk_fma_f32 v[226:227], v[106:107], v[50:51], v[98:99]
	v_cndmask_b32_e64 v72, v52, v60, s[98:99]
	v_cndmask_b32_e64 v73, v53, v61, s[98:99]
	v_cndmask_b32_e64 v74, v54, v62, s[98:99]
	v_cndmask_b32_e64 v75, v55, v63, s[98:99]
	v_cndmask_b32_e64 v76, v48, v56, s[98:99]
	v_cndmask_b32_e64 v77, v49, v57, s[98:99]
	v_cndmask_b32_e64 v78, v50, v58, s[98:99]
	v_cndmask_b32_e64 v79, v51, v59, s[98:99]
	v_fmac_f32_dpp v220, v72, v116 row_ror:1 row_mask:0xf bank_mask:0xf
	v_fmac_f32_dpp v221, v73, v117 row_ror:1 row_mask:0xf bank_mask:0xf
	v_fmac_f32_dpp v222, v74, v118 row_ror:1 row_mask:0xf bank_mask:0xf
	v_fmac_f32_dpp v223, v75, v119 row_ror:1 row_mask:0xf bank_mask:0xf
	v_fmac_f32_dpp v224, v76, v112 row_ror:1 row_mask:0xf bank_mask:0xf
	v_fmac_f32_dpp v225, v77, v113 row_ror:1 row_mask:0xf bank_mask:0xf
	v_fmac_f32_dpp v226, v78, v114 row_ror:1 row_mask:0xf bank_mask:0xf
	v_fmac_f32_dpp v227, v79, v115 row_ror:1 row_mask:0xf bank_mask:0xf
	v_cndmask_b32_e64 v72, v60, v52, s[40:41]
	v_cndmask_b32_e64 v73, v61, v53, s[40:41]
	v_cndmask_b32_e64 v74, v62, v54, s[40:41]
	v_cndmask_b32_e64 v75, v63, v55, s[40:41]
	v_cndmask_b32_e64 v76, v56, v48, s[40:41]
	v_cndmask_b32_e64 v77, v57, v49, s[40:41]
	v_cndmask_b32_e64 v78, v58, v50, s[40:41]
	v_cndmask_b32_e64 v79, v59, v51, s[40:41]
	v_fmac_f32_dpp v220, v72, v124 row_ror:2 row_mask:0xf bank_mask:0xf
	v_fmac_f32_dpp v221, v73, v125 row_ror:2 row_mask:0xf bank_mask:0xf
	v_fmac_f32_dpp v222, v74, v126 row_ror:2 row_mask:0xf bank_mask:0xf
	v_fmac_f32_dpp v223, v75, v127 row_ror:2 row_mask:0xf bank_mask:0xf
	v_fmac_f32_dpp v224, v76, v120 row_ror:2 row_mask:0xf bank_mask:0xf
	v_fmac_f32_dpp v225, v77, v121 row_ror:2 row_mask:0xf bank_mask:0xf
	v_fmac_f32_dpp v226, v78, v122 row_ror:2 row_mask:0xf bank_mask:0xf
	v_fmac_f32_dpp v227, v79, v123 row_ror:2 row_mask:0xf bank_mask:0xf
	v_pk_mul_f32 v[190:191], v[220:221], s[100:101] op_sel_hi:[1,0]
	v_pk_mul_f32 v[250:251], v[222:223], s[100:101] op_sel_hi:[1,0]
	v_exp_f32_e32 v190, v190
	v_exp_f32_e32 v191, v191
	v_exp_f32_e32 v250, v250
	v_exp_f32_e32 v251, v251
	v_pk_mul_f32 v[220:221], v[220:221], v[224:225]
	v_pk_mul_f32 v[222:223], v[222:223], v[226:227]
	v_pk_add_f32 v[190:191], v[190:191], 1.0 op_sel_hi:[1,0]
	v_pk_add_f32 v[250:251], v[250:251], 1.0 op_sel_hi:[1,0]
	v_rcp_f32_e32 v190, v190
	v_rcp_f32_e32 v191, v191
	v_rcp_f32_e32 v250, v250
	v_rcp_f32_e32 v251, v251
	v_pk_mul_f32 v[220:221], v[220:221], v[190:191]
	v_pk_mul_f32 v[222:223], v[222:223], v[250:251]
	v_cvt_pk_bf16_f32 v196, v220, v221
	v_cvt_pk_bf16_f32 v197, v222, v223
	v_add_u32_e32 v243, 0x16000, v239
	global_store_dwordx4 v243, v[194:197], s[24:25]
	v_pk_fma_f32 v[220:221], v[108:109], v[44:45], v[100:101]
	v_pk_fma_f32 v[222:223], v[110:111], v[46:47], v[102:103]
	v_pk_fma_f32 v[224:225], v[104:105], v[40:41], v[96:97]
	v_pk_fma_f32 v[226:227], v[106:107], v[42:43], v[98:99]
	v_cndmask_b32_e64 v72, v44, v52, s[98:99]
	v_cndmask_b32_e64 v73, v45, v53, s[98:99]
	v_cndmask_b32_e64 v74, v46, v54, s[98:99]
	v_cndmask_b32_e64 v75, v47, v55, s[98:99]
	v_cndmask_b32_e64 v76, v40, v48, s[98:99]
	v_cndmask_b32_e64 v77, v41, v49, s[98:99]
	v_cndmask_b32_e64 v78, v42, v50, s[98:99]
	v_cndmask_b32_e64 v79, v43, v51, s[98:99]
	v_fmac_f32_dpp v220, v72, v116 row_ror:1 row_mask:0xf bank_mask:0xf
	v_fmac_f32_dpp v221, v73, v117 row_ror:1 row_mask:0xf bank_mask:0xf
	v_fmac_f32_dpp v222, v74, v118 row_ror:1 row_mask:0xf bank_mask:0xf
	v_fmac_f32_dpp v223, v75, v119 row_ror:1 row_mask:0xf bank_mask:0xf
	v_fmac_f32_dpp v224, v76, v112 row_ror:1 row_mask:0xf bank_mask:0xf
	v_fmac_f32_dpp v225, v77, v113 row_ror:1 row_mask:0xf bank_mask:0xf
	v_fmac_f32_dpp v226, v78, v114 row_ror:1 row_mask:0xf bank_mask:0xf
	v_fmac_f32_dpp v227, v79, v115 row_ror:1 row_mask:0xf bank_mask:0xf
	v_cndmask_b32_e64 v72, v52, v44, s[40:41]
	v_cndmask_b32_e64 v73, v53, v45, s[40:41]
	v_cndmask_b32_e64 v74, v54, v46, s[40:41]
	v_cndmask_b32_e64 v75, v55, v47, s[40:41]
	v_cndmask_b32_e64 v76, v48, v40, s[40:41]
	v_cndmask_b32_e64 v77, v49, v41, s[40:41]
	v_cndmask_b32_e64 v78, v50, v42, s[40:41]
	v_cndmask_b32_e64 v79, v51, v43, s[40:41]
	v_fmac_f32_dpp v220, v72, v124 row_ror:2 row_mask:0xf bank_mask:0xf
	v_fmac_f32_dpp v221, v73, v125 row_ror:2 row_mask:0xf bank_mask:0xf
	v_fmac_f32_dpp v222, v74, v126 row_ror:2 row_mask:0xf bank_mask:0xf
; __device__ __forceinline__ unsigned cvt_pk_bf16(float lo, float hi) { unsigned r; asm volatile("v_cvt_pk_bf16_f32 %0, %1, %2" : "=v"(r) : "v"(lo), "v"(hi)); return r; }
; __device__ __forceinline__ float dpp_ror1(float x) { return __int_as_float(__builtin_amdgcn_update_dpp(0, __float_as_int(x), 0x121, 0xf, 0xf, false)); }
; __device__ __forceinline__ float dpp_ror2(float x) { return __int_as_float(__builtin_amdgcn_update_dpp(0, __float_as_int(x), 0x122, 0xf, 0xf, false)); }
;     __device__ __forceinline__ void operator()(const f32x4 (&acc)[2][2][4][2], const Unit& u, int wr, int wc, int fr, int fq) const {
;     ...
;                 for (int m = 0; m < 4; ++m) {
;                     f32x4 cur[2], h[2];
; #pragma unroll
;                     for (int bj = 0; bj < 2; ++bj) { cur[bj] = acc[ai][bj][m][n] * rs[ai][m]; f32x4 x1, x2;
; #pragma unroll
;                         for (int e = 0; e < 4; ++e) { const float c1 = dpp_ror1(cur[bj][e]), p1 = dpp_ror1(pg[bj][e]), c2 = dpp_ror2(cur[bj][e]), p2 = dpp_ror2(pg[bj][e]);
;                             x1[e] = fr >= 1 ? c1 : p1; x2[e] = fr >= 2 ? c2 : p2; }
;                         h[bj] = bb[bj] + w0[bj] * x2 + w1[bj] * x1 + w2[bj] * cur[bj]; }
;                     if (ai == 0 && wr == 0 && m == 0 && fr < 2) {
;                         *(f32x4*)(hc0 + (size_t)(u.pm * 2 + fr) * FF2 + gcol + 4 * n) = h[0]; *(f32x4*)(hc0 + (size_t)(u.pm * 2 + fr) * FF2 + FF + gcol + 4 * n) = h[1]; }
;                     f32x4 a;
; #pragma unroll
;                     for (int e = 0; e < 4; ++e) { const float g = h[0][e]; a[e] = g * __builtin_amdgcn_rcpf(1.0f + __builtin_amdgcn_exp2f(-1.4426950408889634f * g)) * h[1][e]; }
;                     const unsigned p0 = cvt_pk_bf16(a[0], a[1]), p1 = cvt_pk_bf16(a[2], a[3]);
;                     if (n == 0) { pk_lo[ai][m][0] = p0; pk_lo[ai][m][1] = p1; }
;                     else { u32x4 w; w.x = pk_lo[ai][m][0]; w.y = pk_lo[ai][m][1]; w.z = p0; w.w = p1;
;                         *(u32x4*)(act + (size_t)(u.pm * BM + ai * HALF + wr * 64 + m * 16 + fr) * FF + gcol) = w; }
	v_fmac_f32_dpp v223, v75, v127 row_ror:2 row_mask:0xf bank_mask:0xf
	v_fmac_f32_dpp v224, v76, v120 row_ror:2 row_mask:0xf bank_mask:0xf
	v_fmac_f32_dpp v225, v77, v121 row_ror:2 row_mask:0xf bank_mask:0xf
	v_fmac_f32_dpp v226, v78, v122 row_ror:2 row_mask:0xf bank_mask:0xf
	v_fmac_f32_dpp v227, v79, v123 row_ror:2 row_mask:0xf bank_mask:0xf
	v_pk_mul_f32 v[190:191], v[220:221], s[100:101] op_sel_hi:[1,0]
	v_pk_mul_f32 v[250:251], v[222:223], s[100:101] op_sel_hi:[1,0]
	v_exp_f32_e32 v190, v190
	v_exp_f32_e32 v191, v191
	v_exp_f32_e32 v250, v250
	v_exp_f32_e32 v251, v251
	v_pk_mul_f32 v[220:221], v[220:221], v[224:225]
	v_pk_mul_f32 v[222:223], v[222:223], v[226:227]
	v_pk_add_f32 v[190:191], v[190:191], 1.0 op_sel_hi:[1,0]
	v_pk_add_f32 v[250:251], v[250:251], 1.0 op_sel_hi:[1,0]
	v_rcp_f32_e32 v190, v190
	v_rcp_f32_e32 v191, v191
	v_rcp_f32_e32 v250, v250
	v_rcp_f32_e32 v251, v251
	v_pk_mul_f32 v[220:221], v[220:221], v[190:191]
	v_pk_mul_f32 v[222:223], v[222:223], v[250:251]
	v_cvt_pk_bf16_f32 v200, v220, v221
	v_cvt_pk_bf16_f32 v201, v222, v223
	v_add_u32_e32 v243, 0x2c000, v239
	global_store_dwordx4 v243, v[198:201], s[24:25]
	v_pk_fma_f32 v[220:221], v[108:109], v[36:37], v[100:101]
	v_pk_fma_f32 v[222:223], v[110:111], v[38:39], v[102:103]
	v_pk_fma_f32 v[224:225], v[104:105], v[32:33], v[96:97]
	v_pk_fma_f32 v[226:227], v[106:107], v[34:35], v[98:99]
	v_cndmask_b32_e64 v72, v36, v44, s[98:99]
	v_cndmask_b32_e64 v73, v37, v45, s[98:99]
	v_cndmask_b32_e64 v74, v38, v46, s[98:99]
	v_cndmask_b32_e64 v75, v39, v47, s[98:99]
	v_cndmask_b32_e64 v76, v32, v40, s[98:99]
	v_cndmask_b32_e64 v77, v33, v41, s[98:99]
	v_cndmask_b32_e64 v78, v34, v42, s[98:99]
	v_cndmask_b32_e64 v79, v35, v43, s[98:99]
	v_fmac_f32_dpp v220, v72, v116 row_ror:1 row_mask:0xf bank_mask:0xf
	v_fmac_f32_dpp v221, v73, v117 row_ror:1 row_mask:0xf bank_mask:0xf
	v_fmac_f32_dpp v222, v74, v118 row_ror:1 row_mask:0xf bank_mask:0xf
	v_fmac_f32_dpp v223, v75, v119 row_ror:1 row_mask:0xf bank_mask:0xf
	v_fmac_f32_dpp v224, v76, v112 row_ror:1 row_mask:0xf bank_mask:0xf
	v_fmac_f32_dpp v225, v77, v113 row_ror:1 row_mask:0xf bank_mask:0xf
	v_fmac_f32_dpp v226, v78, v114 row_ror:1 row_mask:0xf bank_mask:0xf
	v_fmac_f32_dpp v227, v79, v115 row_ror:1 row_mask:0xf bank_mask:0xf
	v_cndmask_b32_e64 v72, v44, v36, s[40:41]
	v_cndmask_b32_e64 v73, v45, v37, s[40:41]
	v_cndmask_b32_e64 v74, v46, v38, s[40:41]
	v_cndmask_b32_e64 v75, v47, v39, s[40:41]
	v_cndmask_b32_e64 v76, v40, v32, s[40:41]
	v_cndmask_b32_e64 v77, v41, v33, s[40:41]
	v_cndmask_b32_e64 v78, v42, v34, s[40:41]
	v_cndmask_b32_e64 v79, v43, v35, s[40:41]
	v_fmac_f32_dpp v220, v72, v124 row_ror:2 row_mask:0xf bank_mask:0xf
	v_fmac_f32_dpp v221, v73, v125 row_ror:2 row_mask:0xf bank_mask:0xf
	v_fmac_f32_dpp v222, v74, v126 row_ror:2 row_mask:0xf bank_mask:0xf
	v_fmac_f32_dpp v223, v75, v127 row_ror:2 row_mask:0xf bank_mask:0xf
	v_fmac_f32_dpp v224, v76, v120 row_ror:2 row_mask:0xf bank_mask:0xf
	v_fmac_f32_dpp v225, v77, v121 row_ror:2 row_mask:0xf bank_mask:0xf
	v_fmac_f32_dpp v226, v78, v122 row_ror:2 row_mask:0xf bank_mask:0xf
	v_fmac_f32_dpp v227, v79, v123 row_ror:2 row_mask:0xf bank_mask:0xf
	v_pk_mul_f32 v[190:191], v[220:221], s[100:101] op_sel_hi:[1,0]
	v_pk_mul_f32 v[250:251], v[222:223], s[100:101] op_sel_hi:[1,0]
	v_exp_f32_e32 v190, v190
	v_exp_f32_e32 v191, v191
	v_exp_f32_e32 v250, v250
	v_exp_f32_e32 v251, v251
	v_pk_mul_f32 v[220:221], v[220:221], v[224:225]
	v_pk_mul_f32 v[222:223], v[222:223], v[226:227]
	v_pk_add_f32 v[190:191], v[190:191], 1.0 op_sel_hi:[1,0]
	v_pk_add_f32 v[250:251], v[250:251], 1.0 op_sel_hi:[1,0]
	v_rcp_f32_e32 v190, v190
	v_rcp_f32_e32 v191, v191
	v_rcp_f32_e32 v250, v250
	v_rcp_f32_e32 v251, v251
	v_pk_mul_f32 v[220:221], v[220:221], v[190:191]
	v_pk_mul_f32 v[222:223], v[222:223], v[250:251]
	v_cvt_pk_bf16_f32 v204, v220, v221
	v_cvt_pk_bf16_f32 v205, v222, v223
	v_add_u32_e32 v243, 0x42000, v239
	global_store_dwordx4 v243, v[202:205], s[24:25]
	s_and_b64 vcc, exec, s[46:47]
	s_cbranch_vccz .Lp7_nopf
	s_cmp_eq_u32 s10, s71
	s_cbranch_scc1 .Lp7_nopf
	s_lshl_b32 s78, s10, 8
	s_add_i32 s78, s78, s8
	s_mov_b32 s79, 1
	v_or_b32_e32 v229, s78, v209
	v_lshlrev_b32_e32 v229, 6, v229
	v_add_u32_e32 v231, 0x2000, v229
	global_load_dwordx4 v[60:63], v229, s[26:27]
	global_load_dwordx4 v[52:55], v229, s[26:27] offset:16
	global_load_dwordx4 v[44:47], v229, s[26:27] offset:32
	global_load_dwordx4 v[36:39], v229, s[26:27] offset:48
	global_load_dwordx4 v[56:59], v231, s[26:27]
	global_load_dwordx4 v[48:51], v231, s[26:27] offset:16
	global_load_dwordx4 v[40:43], v231, s[26:27] offset:32
	global_load_dwordx4 v[32:35], v231, s[26:27] offset:48
